# inproj1 main loop hand-rewritten like inproj0 (DMA issue spread, pipelined LDS fragment reads)
# speedup vs baseline: 1.0185x; 1.0185x over previous
.LBB0_430:
	s_ashr_i32 s1, s64, 31
	s_lshr_b32 s1, s1, 23
	s_add_i32 s1, s64, s1
	s_ashr_i32 s1, s1, 9
	s_and_b32 s0, s64, 7
	s_lshl_b32 s1, s1, 3
	s_or_b32 s38, s1, s0
	s_mul_hi_i32 s66, s38, 0x2aaaaaab
	s_lshr_b32 s0, s66, 31
	s_add_i32 s66, s66, s0
	s_lshl_b32 s0, s66, 3
	s_bfe_u32 s1, s64, 0x30003
	s_or_b32 s0, s0, s1
	s_mul_i32 s1, s66, 6
	s_sub_i32 s65, s38, s1
	s_lshl_b32 s1, s65, 3
	s_bfe_u32 s33, s64, 0x30006
	s_or_b32 s4, s1, s33
	s_ashr_i32 s1, s0, 31
	s_ashr_i32 s5, s4, 31
	s_lshl_b64 s[54:55], s[4:5], 18
	s_lshl_b64 s[56:57], s[0:1], 18
	s_barrier
	s_add_u32 s84, s50, 0x3a00000
	s_addc_u32 s85, s51, 0
	s_add_u32 s84, s84, s56
	s_addc_u32 s85, s85, s57
	s_add_u32 s86, s50, s54
	s_addc_u32 s87, s51, s55
	s_lshl_b64 s[54:55], s[0:1], 17
	v_readfirstlane_b32 s88, v129
	v_and_b32_e32 v92, 15, v131
	v_bfe_u32 v93, v131, 4, 2
	v_bfe_u32 v94, v131, 1, 3
	v_xor_b32_e32 v94, v93, v94
	v_lshlrev_b32_e32 v94, 4, v94
	v_lshl_or_b32 v208, v92, 7, v94
	v_xor_b32_e32 v210, 64, v208
	v_lshrrev_b32_e32 v94, 6, v131
	v_lshl_add_u32 v204, v94, 12, v208
	v_lshl_add_u32 v206, v94, 12, v210
	v_bfe_u32 v92, v131, 4, 3
	v_and_b32_e32 v93, 7, v131
	v_xor_b32_e32 v92, v92, v93
	v_lshlrev_b32_e32 v92, 4, v92
	v_lshrrev_b32_e32 v93, 3, v131
	v_lshl_or_b32 v212, v93, 11, v92
	v_add_u32_e32 v214, 65536, v212
	v_add_u32_e32 v216, 131072, v212
	v_add_u32_e32 v218, 196608, v212
	s_add_u32 m0, s88, 0
	v_mov_b32_e32 v32, 0
	v_mov_b32_e32 v33, 0
	global_load_lds_dwordx4 v212, s[84:85]
	s_add_u32 m0, s88, 4096
	v_mov_b32_e32 v34, 0
	v_mov_b32_e32 v35, 0
	global_load_lds_dwordx4 v214, s[84:85]
	s_add_u32 m0, s88, 8192
	v_mov_b32_e32 v36, 0
	v_mov_b32_e32 v37, 0
	global_load_lds_dwordx4 v216, s[84:85]
	s_add_u32 m0, s88, 12288
	v_mov_b32_e32 v38, 0
	v_mov_b32_e32 v39, 0
	global_load_lds_dwordx4 v218, s[84:85]
	s_add_u32 s84, s84, 128
	s_addc_u32 s85, s85, 0
	s_add_u32 m0, s88, 16384
	v_mov_b32_e32 v40, 0
	v_mov_b32_e32 v41, 0
	global_load_lds_dwordx4 v212, s[86:87]
	s_add_u32 m0, s88, 20480
	v_mov_b32_e32 v42, 0
	v_mov_b32_e32 v43, 0
	global_load_lds_dwordx4 v214, s[86:87]
	s_add_u32 m0, s88, 24576
	v_mov_b32_e32 v44, 0
	v_mov_b32_e32 v45, 0
	global_load_lds_dwordx4 v216, s[86:87]
	s_add_u32 m0, s88, 28672
	v_mov_b32_e32 v46, 0
	v_mov_b32_e32 v47, 0
	global_load_lds_dwordx4 v218, s[86:87]
	s_add_u32 s86, s86, 128
	s_addc_u32 s87, s87, 0
	s_add_u32 m0, s88, 32768
	v_mov_b32_e32 v48, 0
	v_mov_b32_e32 v49, 0
	global_load_lds_dwordx4 v212, s[84:85]
	s_add_u32 m0, s88, 36864
	v_mov_b32_e32 v50, 0
	v_mov_b32_e32 v51, 0
	global_load_lds_dwordx4 v214, s[84:85]
	s_add_u32 m0, s88, 40960
	v_mov_b32_e32 v52, 0
	v_mov_b32_e32 v53, 0
	global_load_lds_dwordx4 v216, s[84:85]
	s_add_u32 m0, s88, 45056
	v_mov_b32_e32 v54, 0
	v_mov_b32_e32 v55, 0
	global_load_lds_dwordx4 v218, s[84:85]
	s_add_u32 s84, s84, 128
	s_addc_u32 s85, s85, 0
	s_add_u32 m0, s88, 49152
	v_mov_b32_e32 v56, 0
	v_mov_b32_e32 v57, 0
	global_load_lds_dwordx4 v212, s[86:87]
	s_add_u32 m0, s88, 53248
	v_mov_b32_e32 v58, 0
	v_mov_b32_e32 v59, 0
	global_load_lds_dwordx4 v214, s[86:87]
	s_add_u32 m0, s88, 57344
	v_mov_b32_e32 v60, 0
	v_mov_b32_e32 v61, 0
	global_load_lds_dwordx4 v216, s[86:87]
	s_add_u32 m0, s88, 61440
	v_mov_b32_e32 v62, 0
	v_mov_b32_e32 v63, 0
	global_load_lds_dwordx4 v218, s[86:87]
	s_add_u32 s86, s86, 128
	s_addc_u32 s87, s87, 0
	v_mov_b32_e32 v4, 0
	v_mov_b32_e32 v5, 0
	v_mov_b32_e32 v6, 0
	v_mov_b32_e32 v7, 0
	v_mov_b32_e32 v12, 0
	v_mov_b32_e32 v13, 0
	v_mov_b32_e32 v14, 0
	v_mov_b32_e32 v15, 0
	v_mov_b32_e32 v16, 0
	v_mov_b32_e32 v17, 0
	v_mov_b32_e32 v18, 0
	v_mov_b32_e32 v19, 0
	v_mov_b32_e32 v20, 0
	v_mov_b32_e32 v21, 0
	v_mov_b32_e32 v22, 0
	v_mov_b32_e32 v23, 0
	v_mov_b32_e32 v0, 0
	v_mov_b32_e32 v1, 0
	v_mov_b32_e32 v2, 0
	v_mov_b32_e32 v3, 0
	v_mov_b32_e32 v8, 0
	v_mov_b32_e32 v9, 0
	v_mov_b32_e32 v10, 0
	v_mov_b32_e32 v11, 0
	v_mov_b32_e32 v24, 0
	v_mov_b32_e32 v25, 0
	v_mov_b32_e32 v26, 0
	v_mov_b32_e32 v27, 0
	v_mov_b32_e32 v28, 0
	v_mov_b32_e32 v29, 0
	v_mov_b32_e32 v30, 0
	v_mov_b32_e32 v31, 0
	s_waitcnt vmcnt(8)
	s_barrier
	ds_read_b128 v[76:79], v204 offset:0
	ds_read_b128 v[80:83], v204 offset:2048
	ds_read_b128 v[92:95], v208 offset:16384
	ds_read_b128 v[96:99], v208 offset:18432
	ds_read_b128 v[100:103], v208 offset:20480
	ds_read_b128 v[104:107], v208 offset:22528
	ds_read_b128 v[108:111], v208 offset:24576
	ds_read_b128 v[112:115], v208 offset:26624
	ds_read_b128 v[116:119], v208 offset:28672
	s_waitcnt lgkmcnt(6)
	v_mfma_f32_16x16x32_bf16 v[32:35], v[76:79], v[92:95], v[32:35]
	v_mfma_f32_16x16x32_bf16 v[4:7], v[80:83], v[92:95], v[4:7]
	ds_read_b128 v[120:123], v208 offset:30720
	s_waitcnt lgkmcnt(6)
	v_mfma_f32_16x16x32_bf16 v[36:39], v[76:79], v[96:99], v[36:39]
	v_mfma_f32_16x16x32_bf16 v[12:15], v[80:83], v[96:99], v[12:15]
	ds_read_b128 v[84:87], v206 offset:0
	ds_read_b128 v[88:91], v206 offset:2048
	ds_read_b128 v[124:127], v210 offset:16384
	s_waitcnt lgkmcnt(8)
	v_mfma_f32_16x16x32_bf16 v[40:43], v[76:79], v[100:103], v[40:43]
	v_mfma_f32_16x16x32_bf16 v[16:19], v[80:83], v[100:103], v[16:19]
	ds_read_b128 v[140:143], v210 offset:18432
	s_waitcnt lgkmcnt(8)
	v_mfma_f32_16x16x32_bf16 v[44:47], v[76:79], v[104:107], v[44:47]
	v_mfma_f32_16x16x32_bf16 v[20:23], v[80:83], v[104:107], v[20:23]
	ds_read_b128 v[144:147], v210 offset:20480
	s_waitcnt lgkmcnt(8)
	v_mfma_f32_16x16x32_bf16 v[48:51], v[76:79], v[108:111], v[48:51]
	v_mfma_f32_16x16x32_bf16 v[0:3], v[80:83], v[108:111], v[0:3]
	ds_read_b128 v[148:151], v210 offset:22528
	s_waitcnt lgkmcnt(8)
	v_mfma_f32_16x16x32_bf16 v[52:55], v[76:79], v[112:115], v[52:55]
	v_mfma_f32_16x16x32_bf16 v[8:11], v[80:83], v[112:115], v[8:11]
	ds_read_b128 v[92:95], v210 offset:24576
	s_waitcnt lgkmcnt(8)
	v_mfma_f32_16x16x32_bf16 v[56:59], v[76:79], v[116:119], v[56:59]
	v_mfma_f32_16x16x32_bf16 v[24:27], v[80:83], v[116:119], v[24:27]
	ds_read_b128 v[96:99], v210 offset:26624
	s_waitcnt lgkmcnt(8)
	v_mfma_f32_16x16x32_bf16 v[60:63], v[76:79], v[120:123], v[60:63]
	v_mfma_f32_16x16x32_bf16 v[28:31], v[80:83], v[120:123], v[28:31]
	ds_read_b128 v[100:103], v210 offset:28672
	s_waitcnt lgkmcnt(6)
	v_mfma_f32_16x16x32_bf16 v[32:35], v[84:87], v[124:127], v[32:35]
	v_mfma_f32_16x16x32_bf16 v[4:7], v[88:91], v[124:127], v[4:7]
	ds_read_b128 v[104:107], v210 offset:30720
	s_waitcnt vmcnt(0) lgkmcnt(0)
	s_barrier
	s_add_u32 m0, s88, 0
	s_nop 0
	global_load_lds_dwordx4 v212, s[84:85]
	s_waitcnt lgkmcnt(6)
	v_mfma_f32_16x16x32_bf16 v[36:39], v[84:87], v[140:143], v[36:39]
	v_mfma_f32_16x16x32_bf16 v[12:15], v[88:91], v[140:143], v[12:15]
	ds_read_b128 v[76:79], v204 offset:32768
	ds_read_b128 v[80:83], v204 offset:34816
	ds_read_b128 v[108:111], v208 offset:49152
	s_add_u32 m0, s88, 4096
	s_nop 0
	global_load_lds_dwordx4 v214, s[84:85]
	s_waitcnt lgkmcnt(8)
	v_mfma_f32_16x16x32_bf16 v[40:43], v[84:87], v[144:147], v[40:43]
	v_mfma_f32_16x16x32_bf16 v[16:19], v[88:91], v[144:147], v[16:19]
	ds_read_b128 v[112:115], v208 offset:51200
	s_add_u32 m0, s88, 8192
	s_nop 0
	global_load_lds_dwordx4 v216, s[84:85]
	s_waitcnt lgkmcnt(8)
	v_mfma_f32_16x16x32_bf16 v[44:47], v[84:87], v[148:151], v[44:47]
	v_mfma_f32_16x16x32_bf16 v[20:23], v[88:91], v[148:151], v[20:23]
	ds_read_b128 v[116:119], v208 offset:53248
	s_add_u32 m0, s88, 12288
	s_nop 0
	global_load_lds_dwordx4 v218, s[84:85]
	s_add_u32 s84, s84, 128
	s_addc_u32 s85, s85, 0
	s_waitcnt lgkmcnt(8)
	v_mfma_f32_16x16x32_bf16 v[48:51], v[84:87], v[92:95], v[48:51]
	v_mfma_f32_16x16x32_bf16 v[0:3], v[88:91], v[92:95], v[0:3]
	ds_read_b128 v[120:123], v208 offset:55296
	s_add_u32 m0, s88, 16384
	s_nop 0
	global_load_lds_dwordx4 v212, s[86:87]
	s_waitcnt lgkmcnt(8)
	v_mfma_f32_16x16x32_bf16 v[52:55], v[84:87], v[96:99], v[52:55]
	v_mfma_f32_16x16x32_bf16 v[8:11], v[88:91], v[96:99], v[8:11]
	ds_read_b128 v[124:127], v208 offset:57344
	s_add_u32 m0, s88, 20480
	s_nop 0
	global_load_lds_dwordx4 v214, s[86:87]
	s_waitcnt lgkmcnt(8)
	v_mfma_f32_16x16x32_bf16 v[56:59], v[84:87], v[100:103], v[56:59]
	v_mfma_f32_16x16x32_bf16 v[24:27], v[88:91], v[100:103], v[24:27]
	ds_read_b128 v[140:143], v208 offset:59392
	s_add_u32 m0, s88, 24576
	s_nop 0
	global_load_lds_dwordx4 v216, s[86:87]
	s_waitcnt lgkmcnt(8)
	v_mfma_f32_16x16x32_bf16 v[60:63], v[84:87], v[104:107], v[60:63]
	v_mfma_f32_16x16x32_bf16 v[28:31], v[88:91], v[104:107], v[28:31]
	ds_read_b128 v[144:147], v208 offset:61440
	s_add_u32 m0, s88, 28672
	s_nop 0
	global_load_lds_dwordx4 v218, s[86:87]
	s_add_u32 s86, s86, 128
	s_addc_u32 s87, s87, 0
	s_waitcnt lgkmcnt(6)
	v_mfma_f32_16x16x32_bf16 v[32:35], v[76:79], v[108:111], v[32:35]
	v_mfma_f32_16x16x32_bf16 v[4:7], v[80:83], v[108:111], v[4:7]
	ds_read_b128 v[148:151], v208 offset:63488
	s_waitcnt lgkmcnt(6)
	v_mfma_f32_16x16x32_bf16 v[36:39], v[76:79], v[112:115], v[36:39]
	v_mfma_f32_16x16x32_bf16 v[12:15], v[80:83], v[112:115], v[12:15]
	ds_read_b128 v[84:87], v206 offset:32768
	ds_read_b128 v[88:91], v206 offset:34816
	ds_read_b128 v[92:95], v210 offset:49152
	s_waitcnt lgkmcnt(8)
	v_mfma_f32_16x16x32_bf16 v[40:43], v[76:79], v[116:119], v[40:43]
	v_mfma_f32_16x16x32_bf16 v[16:19], v[80:83], v[116:119], v[16:19]
	ds_read_b128 v[96:99], v210 offset:51200
	s_waitcnt lgkmcnt(8)
	v_mfma_f32_16x16x32_bf16 v[44:47], v[76:79], v[120:123], v[44:47]
	v_mfma_f32_16x16x32_bf16 v[20:23], v[80:83], v[120:123], v[20:23]
	ds_read_b128 v[100:103], v210 offset:53248
	s_waitcnt lgkmcnt(8)
	v_mfma_f32_16x16x32_bf16 v[48:51], v[76:79], v[124:127], v[48:51]
	v_mfma_f32_16x16x32_bf16 v[0:3], v[80:83], v[124:127], v[0:3]
	ds_read_b128 v[104:107], v210 offset:55296
	s_waitcnt lgkmcnt(8)
	v_mfma_f32_16x16x32_bf16 v[52:55], v[76:79], v[140:143], v[52:55]
	v_mfma_f32_16x16x32_bf16 v[8:11], v[80:83], v[140:143], v[8:11]
	ds_read_b128 v[108:111], v210 offset:57344
	s_waitcnt lgkmcnt(8)
	v_mfma_f32_16x16x32_bf16 v[56:59], v[76:79], v[144:147], v[56:59]
	v_mfma_f32_16x16x32_bf16 v[24:27], v[80:83], v[144:147], v[24:27]
	ds_read_b128 v[112:115], v210 offset:59392
	s_waitcnt lgkmcnt(8)
	v_mfma_f32_16x16x32_bf16 v[60:63], v[76:79], v[148:151], v[60:63]
	v_mfma_f32_16x16x32_bf16 v[28:31], v[80:83], v[148:151], v[28:31]
	ds_read_b128 v[116:119], v210 offset:61440
	s_waitcnt lgkmcnt(6)
	v_mfma_f32_16x16x32_bf16 v[32:35], v[84:87], v[92:95], v[32:35]
	v_mfma_f32_16x16x32_bf16 v[4:7], v[88:91], v[92:95], v[4:7]
	ds_read_b128 v[120:123], v210 offset:63488
	s_waitcnt vmcnt(0) lgkmcnt(0)
	s_barrier
	s_add_u32 m0, s88, 32768
	s_nop 0
	global_load_lds_dwordx4 v212, s[84:85]
	s_waitcnt lgkmcnt(6)
	v_mfma_f32_16x16x32_bf16 v[36:39], v[84:87], v[96:99], v[36:39]
	v_mfma_f32_16x16x32_bf16 v[12:15], v[88:91], v[96:99], v[12:15]
	ds_read_b128 v[76:79], v204 offset:0
	ds_read_b128 v[80:83], v204 offset:2048
	ds_read_b128 v[124:127], v208 offset:16384
	s_add_u32 m0, s88, 36864
	s_nop 0
	global_load_lds_dwordx4 v214, s[84:85]
	s_waitcnt lgkmcnt(8)
	v_mfma_f32_16x16x32_bf16 v[40:43], v[84:87], v[100:103], v[40:43]
	v_mfma_f32_16x16x32_bf16 v[16:19], v[88:91], v[100:103], v[16:19]
	ds_read_b128 v[140:143], v208 offset:18432
	s_add_u32 m0, s88, 40960
	s_nop 0
	global_load_lds_dwordx4 v216, s[84:85]
	s_waitcnt lgkmcnt(8)
	v_mfma_f32_16x16x32_bf16 v[44:47], v[84:87], v[104:107], v[44:47]
	v_mfma_f32_16x16x32_bf16 v[20:23], v[88:91], v[104:107], v[20:23]
	ds_read_b128 v[144:147], v208 offset:20480
	s_add_u32 m0, s88, 45056
	s_nop 0
	global_load_lds_dwordx4 v218, s[84:85]
	s_add_u32 s84, s84, 128
	s_addc_u32 s85, s85, 0
	s_waitcnt lgkmcnt(8)
	v_mfma_f32_16x16x32_bf16 v[48:51], v[84:87], v[108:111], v[48:51]
	v_mfma_f32_16x16x32_bf16 v[0:3], v[88:91], v[108:111], v[0:3]
	ds_read_b128 v[148:151], v208 offset:22528
	s_add_u32 m0, s88, 49152
	s_nop 0
	global_load_lds_dwordx4 v212, s[86:87]
	s_waitcnt lgkmcnt(8)
	v_mfma_f32_16x16x32_bf16 v[52:55], v[84:87], v[112:115], v[52:55]
	v_mfma_f32_16x16x32_bf16 v[8:11], v[88:91], v[112:115], v[8:11]
	ds_read_b128 v[92:95], v208 offset:24576
	s_add_u32 m0, s88, 53248
	s_nop 0
	global_load_lds_dwordx4 v214, s[86:87]
	s_waitcnt lgkmcnt(8)
	v_mfma_f32_16x16x32_bf16 v[56:59], v[84:87], v[116:119], v[56:59]
	v_mfma_f32_16x16x32_bf16 v[24:27], v[88:91], v[116:119], v[24:27]
	ds_read_b128 v[96:99], v208 offset:26624
	s_add_u32 m0, s88, 57344
	s_nop 0
	global_load_lds_dwordx4 v216, s[86:87]
	s_waitcnt lgkmcnt(8)
	v_mfma_f32_16x16x32_bf16 v[60:63], v[84:87], v[120:123], v[60:63]
	v_mfma_f32_16x16x32_bf16 v[28:31], v[88:91], v[120:123], v[28:31]
	ds_read_b128 v[100:103], v208 offset:28672
	s_add_u32 m0, s88, 61440
	s_nop 0
	global_load_lds_dwordx4 v218, s[86:87]
	s_add_u32 s86, s86, 128
	s_addc_u32 s87, s87, 0
	s_waitcnt lgkmcnt(6)
	v_mfma_f32_16x16x32_bf16 v[32:35], v[76:79], v[124:127], v[32:35]
	v_mfma_f32_16x16x32_bf16 v[4:7], v[80:83], v[124:127], v[4:7]
	ds_read_b128 v[104:107], v208 offset:30720
	s_waitcnt lgkmcnt(6)
	v_mfma_f32_16x16x32_bf16 v[36:39], v[76:79], v[140:143], v[36:39]
	v_mfma_f32_16x16x32_bf16 v[12:15], v[80:83], v[140:143], v[12:15]
	ds_read_b128 v[84:87], v206 offset:0
	ds_read_b128 v[88:91], v206 offset:2048
	ds_read_b128 v[108:111], v210 offset:16384
	s_waitcnt lgkmcnt(8)
	v_mfma_f32_16x16x32_bf16 v[40:43], v[76:79], v[144:147], v[40:43]
	v_mfma_f32_16x16x32_bf16 v[16:19], v[80:83], v[144:147], v[16:19]
	ds_read_b128 v[112:115], v210 offset:18432
	s_waitcnt lgkmcnt(8)
	v_mfma_f32_16x16x32_bf16 v[44:47], v[76:79], v[148:151], v[44:47]
	v_mfma_f32_16x16x32_bf16 v[20:23], v[80:83], v[148:151], v[20:23]
	ds_read_b128 v[116:119], v210 offset:20480
	s_waitcnt lgkmcnt(8)
	v_mfma_f32_16x16x32_bf16 v[48:51], v[76:79], v[92:95], v[48:51]
	v_mfma_f32_16x16x32_bf16 v[0:3], v[80:83], v[92:95], v[0:3]
	ds_read_b128 v[120:123], v210 offset:22528
	s_waitcnt lgkmcnt(8)
	v_mfma_f32_16x16x32_bf16 v[52:55], v[76:79], v[96:99], v[52:55]
	v_mfma_f32_16x16x32_bf16 v[8:11], v[80:83], v[96:99], v[8:11]
	ds_read_b128 v[124:127], v210 offset:24576
	s_waitcnt lgkmcnt(8)
	v_mfma_f32_16x16x32_bf16 v[56:59], v[76:79], v[100:103], v[56:59]
	v_mfma_f32_16x16x32_bf16 v[24:27], v[80:83], v[100:103], v[24:27]
	ds_read_b128 v[140:143], v210 offset:26624
	s_waitcnt lgkmcnt(8)
	v_mfma_f32_16x16x32_bf16 v[60:63], v[76:79], v[104:107], v[60:63]
	v_mfma_f32_16x16x32_bf16 v[28:31], v[80:83], v[104:107], v[28:31]
	ds_read_b128 v[144:147], v210 offset:28672
	s_waitcnt lgkmcnt(6)
	v_mfma_f32_16x16x32_bf16 v[32:35], v[84:87], v[108:111], v[32:35]
	v_mfma_f32_16x16x32_bf16 v[4:7], v[88:91], v[108:111], v[4:7]
	ds_read_b128 v[148:151], v210 offset:30720
	s_waitcnt vmcnt(0) lgkmcnt(0)
	s_barrier
	s_add_u32 m0, s88, 0
	s_nop 0
	global_load_lds_dwordx4 v212, s[84:85]
	s_waitcnt lgkmcnt(6)
	v_mfma_f32_16x16x32_bf16 v[36:39], v[84:87], v[112:115], v[36:39]
	v_mfma_f32_16x16x32_bf16 v[12:15], v[88:91], v[112:115], v[12:15]
	ds_read_b128 v[76:79], v204 offset:32768
	ds_read_b128 v[80:83], v204 offset:34816
	ds_read_b128 v[92:95], v208 offset:49152
	s_add_u32 m0, s88, 4096
	s_nop 0
	global_load_lds_dwordx4 v214, s[84:85]
	s_waitcnt lgkmcnt(8)
	v_mfma_f32_16x16x32_bf16 v[40:43], v[84:87], v[116:119], v[40:43]
	v_mfma_f32_16x16x32_bf16 v[16:19], v[88:91], v[116:119], v[16:19]
	ds_read_b128 v[96:99], v208 offset:51200
	s_add_u32 m0, s88, 8192
	s_nop 0
	global_load_lds_dwordx4 v216, s[84:85]
	s_waitcnt lgkmcnt(8)
	v_mfma_f32_16x16x32_bf16 v[44:47], v[84:87], v[120:123], v[44:47]
	v_mfma_f32_16x16x32_bf16 v[20:23], v[88:91], v[120:123], v[20:23]
	ds_read_b128 v[100:103], v208 offset:53248
	s_add_u32 m0, s88, 12288
	s_nop 0
	global_load_lds_dwordx4 v218, s[84:85]
	s_add_u32 s84, s84, 128
	s_addc_u32 s85, s85, 0
	s_waitcnt lgkmcnt(8)
	v_mfma_f32_16x16x32_bf16 v[48:51], v[84:87], v[124:127], v[48:51]
	v_mfma_f32_16x16x32_bf16 v[0:3], v[88:91], v[124:127], v[0:3]
	ds_read_b128 v[104:107], v208 offset:55296
	s_add_u32 m0, s88, 16384
	s_nop 0
	global_load_lds_dwordx4 v212, s[86:87]
	s_waitcnt lgkmcnt(8)
	v_mfma_f32_16x16x32_bf16 v[52:55], v[84:87], v[140:143], v[52:55]
	v_mfma_f32_16x16x32_bf16 v[8:11], v[88:91], v[140:143], v[8:11]
	ds_read_b128 v[108:111], v208 offset:57344
	s_add_u32 m0, s88, 20480
	s_nop 0
	global_load_lds_dwordx4 v214, s[86:87]
	s_waitcnt lgkmcnt(8)
	v_mfma_f32_16x16x32_bf16 v[56:59], v[84:87], v[144:147], v[56:59]
	v_mfma_f32_16x16x32_bf16 v[24:27], v[88:91], v[144:147], v[24:27]
	ds_read_b128 v[112:115], v208 offset:59392
	s_add_u32 m0, s88, 24576
	s_nop 0
	global_load_lds_dwordx4 v216, s[86:87]
	s_waitcnt lgkmcnt(8)
	v_mfma_f32_16x16x32_bf16 v[60:63], v[84:87], v[148:151], v[60:63]
	v_mfma_f32_16x16x32_bf16 v[28:31], v[88:91], v[148:151], v[28:31]
	ds_read_b128 v[116:119], v208 offset:61440
	s_add_u32 m0, s88, 28672
	s_nop 0
	global_load_lds_dwordx4 v218, s[86:87]
	s_add_u32 s86, s86, 128
	s_addc_u32 s87, s87, 0
	s_waitcnt lgkmcnt(6)
	v_mfma_f32_16x16x32_bf16 v[32:35], v[76:79], v[92:95], v[32:35]
	v_mfma_f32_16x16x32_bf16 v[4:7], v[80:83], v[92:95], v[4:7]
	ds_read_b128 v[120:123], v208 offset:63488
	s_waitcnt lgkmcnt(6)
	v_mfma_f32_16x16x32_bf16 v[36:39], v[76:79], v[96:99], v[36:39]
	v_mfma_f32_16x16x32_bf16 v[12:15], v[80:83], v[96:99], v[12:15]
	ds_read_b128 v[84:87], v206 offset:32768
	ds_read_b128 v[88:91], v206 offset:34816
	ds_read_b128 v[124:127], v210 offset:49152
	s_waitcnt lgkmcnt(8)
	v_mfma_f32_16x16x32_bf16 v[40:43], v[76:79], v[100:103], v[40:43]
	v_mfma_f32_16x16x32_bf16 v[16:19], v[80:83], v[100:103], v[16:19]
	ds_read_b128 v[140:143], v210 offset:51200
	s_waitcnt lgkmcnt(8)
	v_mfma_f32_16x16x32_bf16 v[44:47], v[76:79], v[104:107], v[44:47]
	v_mfma_f32_16x16x32_bf16 v[20:23], v[80:83], v[104:107], v[20:23]
	ds_read_b128 v[144:147], v210 offset:53248
	s_waitcnt lgkmcnt(8)
	v_mfma_f32_16x16x32_bf16 v[48:51], v[76:79], v[108:111], v[48:51]
	v_mfma_f32_16x16x32_bf16 v[0:3], v[80:83], v[108:111], v[0:3]
	ds_read_b128 v[148:151], v210 offset:55296
	s_waitcnt lgkmcnt(8)
	v_mfma_f32_16x16x32_bf16 v[52:55], v[76:79], v[112:115], v[52:55]
	v_mfma_f32_16x16x32_bf16 v[8:11], v[80:83], v[112:115], v[8:11]
	ds_read_b128 v[92:95], v210 offset:57344
	s_waitcnt lgkmcnt(8)
	v_mfma_f32_16x16x32_bf16 v[56:59], v[76:79], v[116:119], v[56:59]
	v_mfma_f32_16x16x32_bf16 v[24:27], v[80:83], v[116:119], v[24:27]
	ds_read_b128 v[96:99], v210 offset:59392
	s_waitcnt lgkmcnt(8)
	v_mfma_f32_16x16x32_bf16 v[60:63], v[76:79], v[120:123], v[60:63]
	v_mfma_f32_16x16x32_bf16 v[28:31], v[80:83], v[120:123], v[28:31]
	ds_read_b128 v[100:103], v210 offset:61440
	s_waitcnt lgkmcnt(6)
	v_mfma_f32_16x16x32_bf16 v[32:35], v[84:87], v[124:127], v[32:35]
	v_mfma_f32_16x16x32_bf16 v[4:7], v[88:91], v[124:127], v[4:7]
	ds_read_b128 v[104:107], v210 offset:63488
	s_waitcnt vmcnt(0) lgkmcnt(0)
	s_barrier
	s_add_u32 m0, s88, 32768
	s_nop 0
	global_load_lds_dwordx4 v212, s[84:85]
	s_waitcnt lgkmcnt(6)
	v_mfma_f32_16x16x32_bf16 v[36:39], v[84:87], v[140:143], v[36:39]
	v_mfma_f32_16x16x32_bf16 v[12:15], v[88:91], v[140:143], v[12:15]
	ds_read_b128 v[76:79], v204 offset:0
	ds_read_b128 v[80:83], v204 offset:2048
	ds_read_b128 v[108:111], v208 offset:16384
	s_add_u32 m0, s88, 36864
	s_nop 0
	global_load_lds_dwordx4 v214, s[84:85]
	s_waitcnt lgkmcnt(8)
	v_mfma_f32_16x16x32_bf16 v[40:43], v[84:87], v[144:147], v[40:43]
	v_mfma_f32_16x16x32_bf16 v[16:19], v[88:91], v[144:147], v[16:19]
	ds_read_b128 v[112:115], v208 offset:18432
	s_add_u32 m0, s88, 40960
	s_nop 0
	global_load_lds_dwordx4 v216, s[84:85]
	s_waitcnt lgkmcnt(8)
	v_mfma_f32_16x16x32_bf16 v[44:47], v[84:87], v[148:151], v[44:47]
	v_mfma_f32_16x16x32_bf16 v[20:23], v[88:91], v[148:151], v[20:23]
	ds_read_b128 v[116:119], v208 offset:20480
	s_add_u32 m0, s88, 45056
	s_nop 0
	global_load_lds_dwordx4 v218, s[84:85]
	s_add_u32 s84, s84, 128
	s_addc_u32 s85, s85, 0
	s_waitcnt lgkmcnt(8)
	v_mfma_f32_16x16x32_bf16 v[48:51], v[84:87], v[92:95], v[48:51]
	v_mfma_f32_16x16x32_bf16 v[0:3], v[88:91], v[92:95], v[0:3]
	ds_read_b128 v[120:123], v208 offset:22528
	s_add_u32 m0, s88, 49152
	s_nop 0
	global_load_lds_dwordx4 v212, s[86:87]
	s_waitcnt lgkmcnt(8)
	v_mfma_f32_16x16x32_bf16 v[52:55], v[84:87], v[96:99], v[52:55]
	v_mfma_f32_16x16x32_bf16 v[8:11], v[88:91], v[96:99], v[8:11]
	ds_read_b128 v[124:127], v208 offset:24576
	s_add_u32 m0, s88, 53248
	s_nop 0
	global_load_lds_dwordx4 v214, s[86:87]
	s_waitcnt lgkmcnt(8)
	v_mfma_f32_16x16x32_bf16 v[56:59], v[84:87], v[100:103], v[56:59]
	v_mfma_f32_16x16x32_bf16 v[24:27], v[88:91], v[100:103], v[24:27]
	ds_read_b128 v[140:143], v208 offset:26624
	s_add_u32 m0, s88, 57344
	s_nop 0
	global_load_lds_dwordx4 v216, s[86:87]
	s_waitcnt lgkmcnt(8)
	v_mfma_f32_16x16x32_bf16 v[60:63], v[84:87], v[104:107], v[60:63]
	v_mfma_f32_16x16x32_bf16 v[28:31], v[88:91], v[104:107], v[28:31]
	ds_read_b128 v[144:147], v208 offset:28672
	s_add_u32 m0, s88, 61440
	s_nop 0
	global_load_lds_dwordx4 v218, s[86:87]
	s_add_u32 s86, s86, 128
	s_addc_u32 s87, s87, 0
	s_waitcnt lgkmcnt(6)
	v_mfma_f32_16x16x32_bf16 v[32:35], v[76:79], v[108:111], v[32:35]
	v_mfma_f32_16x16x32_bf16 v[4:7], v[80:83], v[108:111], v[4:7]
	ds_read_b128 v[148:151], v208 offset:30720
	s_waitcnt lgkmcnt(6)
	v_mfma_f32_16x16x32_bf16 v[36:39], v[76:79], v[112:115], v[36:39]
	v_mfma_f32_16x16x32_bf16 v[12:15], v[80:83], v[112:115], v[12:15]
	ds_read_b128 v[84:87], v206 offset:0
	ds_read_b128 v[88:91], v206 offset:2048
	ds_read_b128 v[92:95], v210 offset:16384
	s_waitcnt lgkmcnt(8)
	v_mfma_f32_16x16x32_bf16 v[40:43], v[76:79], v[116:119], v[40:43]
	v_mfma_f32_16x16x32_bf16 v[16:19], v[80:83], v[116:119], v[16:19]
	ds_read_b128 v[96:99], v210 offset:18432
	s_waitcnt lgkmcnt(8)
	v_mfma_f32_16x16x32_bf16 v[44:47], v[76:79], v[120:123], v[44:47]
	v_mfma_f32_16x16x32_bf16 v[20:23], v[80:83], v[120:123], v[20:23]
	ds_read_b128 v[100:103], v210 offset:20480
	s_waitcnt lgkmcnt(8)
	v_mfma_f32_16x16x32_bf16 v[48:51], v[76:79], v[124:127], v[48:51]
	v_mfma_f32_16x16x32_bf16 v[0:3], v[80:83], v[124:127], v[0:3]
	ds_read_b128 v[104:107], v210 offset:22528
	s_waitcnt lgkmcnt(8)
	v_mfma_f32_16x16x32_bf16 v[52:55], v[76:79], v[140:143], v[52:55]
	v_mfma_f32_16x16x32_bf16 v[8:11], v[80:83], v[140:143], v[8:11]
	ds_read_b128 v[108:111], v210 offset:24576
	s_waitcnt lgkmcnt(8)
	v_mfma_f32_16x16x32_bf16 v[56:59], v[76:79], v[144:147], v[56:59]
	v_mfma_f32_16x16x32_bf16 v[24:27], v[80:83], v[144:147], v[24:27]
	ds_read_b128 v[112:115], v210 offset:26624
	s_waitcnt lgkmcnt(8)
	v_mfma_f32_16x16x32_bf16 v[60:63], v[76:79], v[148:151], v[60:63]
	v_mfma_f32_16x16x32_bf16 v[28:31], v[80:83], v[148:151], v[28:31]
	ds_read_b128 v[116:119], v210 offset:28672
	s_waitcnt lgkmcnt(6)
	v_mfma_f32_16x16x32_bf16 v[32:35], v[84:87], v[92:95], v[32:35]
	v_mfma_f32_16x16x32_bf16 v[4:7], v[88:91], v[92:95], v[4:7]
	ds_read_b128 v[120:123], v210 offset:30720
	s_waitcnt vmcnt(0) lgkmcnt(0)
	s_barrier
	s_add_u32 m0, s88, 0
	s_nop 0
	global_load_lds_dwordx4 v212, s[84:85]
	s_waitcnt lgkmcnt(6)
	v_mfma_f32_16x16x32_bf16 v[36:39], v[84:87], v[96:99], v[36:39]
	v_mfma_f32_16x16x32_bf16 v[12:15], v[88:91], v[96:99], v[12:15]
	ds_read_b128 v[76:79], v204 offset:32768
	ds_read_b128 v[80:83], v204 offset:34816
	ds_read_b128 v[124:127], v208 offset:49152
	s_add_u32 m0, s88, 4096
	s_nop 0
	global_load_lds_dwordx4 v214, s[84:85]
	s_waitcnt lgkmcnt(8)
	v_mfma_f32_16x16x32_bf16 v[40:43], v[84:87], v[100:103], v[40:43]
	v_mfma_f32_16x16x32_bf16 v[16:19], v[88:91], v[100:103], v[16:19]
	ds_read_b128 v[140:143], v208 offset:51200
	s_add_u32 m0, s88, 8192
	s_nop 0
	global_load_lds_dwordx4 v216, s[84:85]
	s_waitcnt lgkmcnt(8)
	v_mfma_f32_16x16x32_bf16 v[44:47], v[84:87], v[104:107], v[44:47]
	v_mfma_f32_16x16x32_bf16 v[20:23], v[88:91], v[104:107], v[20:23]
	ds_read_b128 v[144:147], v208 offset:53248
	s_add_u32 m0, s88, 12288
	s_nop 0
	global_load_lds_dwordx4 v218, s[84:85]
	s_add_u32 s84, s84, 128
	s_addc_u32 s85, s85, 0
	s_waitcnt lgkmcnt(8)
	v_mfma_f32_16x16x32_bf16 v[48:51], v[84:87], v[108:111], v[48:51]
	v_mfma_f32_16x16x32_bf16 v[0:3], v[88:91], v[108:111], v[0:3]
	ds_read_b128 v[148:151], v208 offset:55296
	s_add_u32 m0, s88, 16384
	s_nop 0
	global_load_lds_dwordx4 v212, s[86:87]
	s_waitcnt lgkmcnt(8)
	v_mfma_f32_16x16x32_bf16 v[52:55], v[84:87], v[112:115], v[52:55]
	v_mfma_f32_16x16x32_bf16 v[8:11], v[88:91], v[112:115], v[8:11]
	ds_read_b128 v[92:95], v208 offset:57344
	s_add_u32 m0, s88, 20480
	s_nop 0
	global_load_lds_dwordx4 v214, s[86:87]
	s_waitcnt lgkmcnt(8)
	v_mfma_f32_16x16x32_bf16 v[56:59], v[84:87], v[116:119], v[56:59]
	v_mfma_f32_16x16x32_bf16 v[24:27], v[88:91], v[116:119], v[24:27]
	ds_read_b128 v[96:99], v208 offset:59392
	s_add_u32 m0, s88, 24576
	s_nop 0
	global_load_lds_dwordx4 v216, s[86:87]
	s_waitcnt lgkmcnt(8)
	v_mfma_f32_16x16x32_bf16 v[60:63], v[84:87], v[120:123], v[60:63]
	v_mfma_f32_16x16x32_bf16 v[28:31], v[88:91], v[120:123], v[28:31]
	ds_read_b128 v[100:103], v208 offset:61440
	s_add_u32 m0, s88, 28672
	s_nop 0
	global_load_lds_dwordx4 v218, s[86:87]
	s_add_u32 s86, s86, 128
	s_addc_u32 s87, s87, 0
	s_waitcnt lgkmcnt(6)
	v_mfma_f32_16x16x32_bf16 v[32:35], v[76:79], v[124:127], v[32:35]
	v_mfma_f32_16x16x32_bf16 v[4:7], v[80:83], v[124:127], v[4:7]
	ds_read_b128 v[104:107], v208 offset:63488
	s_waitcnt lgkmcnt(6)
	v_mfma_f32_16x16x32_bf16 v[36:39], v[76:79], v[140:143], v[36:39]
	v_mfma_f32_16x16x32_bf16 v[12:15], v[80:83], v[140:143], v[12:15]
	ds_read_b128 v[84:87], v206 offset:32768
	ds_read_b128 v[88:91], v206 offset:34816
	ds_read_b128 v[108:111], v210 offset:49152
	s_waitcnt lgkmcnt(8)
	v_mfma_f32_16x16x32_bf16 v[40:43], v[76:79], v[144:147], v[40:43]
	v_mfma_f32_16x16x32_bf16 v[16:19], v[80:83], v[144:147], v[16:19]
	ds_read_b128 v[112:115], v210 offset:51200
	s_waitcnt lgkmcnt(8)
	v_mfma_f32_16x16x32_bf16 v[44:47], v[76:79], v[148:151], v[44:47]
	v_mfma_f32_16x16x32_bf16 v[20:23], v[80:83], v[148:151], v[20:23]
	ds_read_b128 v[116:119], v210 offset:53248
	s_waitcnt lgkmcnt(8)
	v_mfma_f32_16x16x32_bf16 v[48:51], v[76:79], v[92:95], v[48:51]
	v_mfma_f32_16x16x32_bf16 v[0:3], v[80:83], v[92:95], v[0:3]
	ds_read_b128 v[120:123], v210 offset:55296
	s_waitcnt lgkmcnt(8)
	v_mfma_f32_16x16x32_bf16 v[52:55], v[76:79], v[96:99], v[52:55]
	v_mfma_f32_16x16x32_bf16 v[8:11], v[80:83], v[96:99], v[8:11]
	ds_read_b128 v[124:127], v210 offset:57344
	s_waitcnt lgkmcnt(8)
	v_mfma_f32_16x16x32_bf16 v[56:59], v[76:79], v[100:103], v[56:59]
	v_mfma_f32_16x16x32_bf16 v[24:27], v[80:83], v[100:103], v[24:27]
	ds_read_b128 v[140:143], v210 offset:59392
	s_waitcnt lgkmcnt(8)
	v_mfma_f32_16x16x32_bf16 v[60:63], v[76:79], v[104:107], v[60:63]
	v_mfma_f32_16x16x32_bf16 v[28:31], v[80:83], v[104:107], v[28:31]
	ds_read_b128 v[144:147], v210 offset:61440
	s_waitcnt lgkmcnt(6)
	v_mfma_f32_16x16x32_bf16 v[32:35], v[84:87], v[108:111], v[32:35]
	v_mfma_f32_16x16x32_bf16 v[4:7], v[88:91], v[108:111], v[4:7]
	ds_read_b128 v[148:151], v210 offset:63488
	s_waitcnt vmcnt(0) lgkmcnt(0)
	s_barrier
	s_add_u32 m0, s88, 32768
	s_nop 0
	global_load_lds_dwordx4 v212, s[84:85]
	s_waitcnt lgkmcnt(6)
	v_mfma_f32_16x16x32_bf16 v[36:39], v[84:87], v[112:115], v[36:39]
	v_mfma_f32_16x16x32_bf16 v[12:15], v[88:91], v[112:115], v[12:15]
	ds_read_b128 v[76:79], v204 offset:0
	ds_read_b128 v[80:83], v204 offset:2048
	ds_read_b128 v[92:95], v208 offset:16384
	s_add_u32 m0, s88, 36864
	s_nop 0
	global_load_lds_dwordx4 v214, s[84:85]
	s_waitcnt lgkmcnt(8)
	v_mfma_f32_16x16x32_bf16 v[40:43], v[84:87], v[116:119], v[40:43]
	v_mfma_f32_16x16x32_bf16 v[16:19], v[88:91], v[116:119], v[16:19]
	ds_read_b128 v[96:99], v208 offset:18432
	s_add_u32 m0, s88, 40960
	s_nop 0
	global_load_lds_dwordx4 v216, s[84:85]
	s_waitcnt lgkmcnt(8)
	v_mfma_f32_16x16x32_bf16 v[44:47], v[84:87], v[120:123], v[44:47]
	v_mfma_f32_16x16x32_bf16 v[20:23], v[88:91], v[120:123], v[20:23]
	ds_read_b128 v[100:103], v208 offset:20480
	s_add_u32 m0, s88, 45056
	s_nop 0
	global_load_lds_dwordx4 v218, s[84:85]
	s_add_u32 s84, s84, 128
	s_addc_u32 s85, s85, 0
	s_waitcnt lgkmcnt(8)
	v_mfma_f32_16x16x32_bf16 v[48:51], v[84:87], v[124:127], v[48:51]
	v_mfma_f32_16x16x32_bf16 v[0:3], v[88:91], v[124:127], v[0:3]
	ds_read_b128 v[104:107], v208 offset:22528
	s_add_u32 m0, s88, 49152
	s_nop 0
	global_load_lds_dwordx4 v212, s[86:87]
	s_waitcnt lgkmcnt(8)
	v_mfma_f32_16x16x32_bf16 v[52:55], v[84:87], v[140:143], v[52:55]
	v_mfma_f32_16x16x32_bf16 v[8:11], v[88:91], v[140:143], v[8:11]
	ds_read_b128 v[108:111], v208 offset:24576
	s_add_u32 m0, s88, 53248
	s_nop 0
	global_load_lds_dwordx4 v214, s[86:87]
	s_waitcnt lgkmcnt(8)
	v_mfma_f32_16x16x32_bf16 v[56:59], v[84:87], v[144:147], v[56:59]
	v_mfma_f32_16x16x32_bf16 v[24:27], v[88:91], v[144:147], v[24:27]
	ds_read_b128 v[112:115], v208 offset:26624
	s_add_u32 m0, s88, 57344
	s_nop 0
	global_load_lds_dwordx4 v216, s[86:87]
	s_waitcnt lgkmcnt(8)
	v_mfma_f32_16x16x32_bf16 v[60:63], v[84:87], v[148:151], v[60:63]
	v_mfma_f32_16x16x32_bf16 v[28:31], v[88:91], v[148:151], v[28:31]
	ds_read_b128 v[116:119], v208 offset:28672
	s_add_u32 m0, s88, 61440
	s_nop 0
	global_load_lds_dwordx4 v218, s[86:87]
	s_add_u32 s86, s86, 128
	s_addc_u32 s87, s87, 0
	s_waitcnt lgkmcnt(6)
	v_mfma_f32_16x16x32_bf16 v[32:35], v[76:79], v[92:95], v[32:35]
	v_mfma_f32_16x16x32_bf16 v[4:7], v[80:83], v[92:95], v[4:7]
	ds_read_b128 v[120:123], v208 offset:30720
	s_waitcnt lgkmcnt(6)
	v_mfma_f32_16x16x32_bf16 v[36:39], v[76:79], v[96:99], v[36:39]
	v_mfma_f32_16x16x32_bf16 v[12:15], v[80:83], v[96:99], v[12:15]
	ds_read_b128 v[84:87], v206 offset:0
	ds_read_b128 v[88:91], v206 offset:2048
	ds_read_b128 v[124:127], v210 offset:16384
	s_waitcnt lgkmcnt(8)
	v_mfma_f32_16x16x32_bf16 v[40:43], v[76:79], v[100:103], v[40:43]
	v_mfma_f32_16x16x32_bf16 v[16:19], v[80:83], v[100:103], v[16:19]
	ds_read_b128 v[140:143], v210 offset:18432
	s_waitcnt lgkmcnt(8)
	v_mfma_f32_16x16x32_bf16 v[44:47], v[76:79], v[104:107], v[44:47]
	v_mfma_f32_16x16x32_bf16 v[20:23], v[80:83], v[104:107], v[20:23]
	ds_read_b128 v[144:147], v210 offset:20480
	s_waitcnt lgkmcnt(8)
	v_mfma_f32_16x16x32_bf16 v[48:51], v[76:79], v[108:111], v[48:51]
	v_mfma_f32_16x16x32_bf16 v[0:3], v[80:83], v[108:111], v[0:3]
	ds_read_b128 v[148:151], v210 offset:22528
	s_waitcnt lgkmcnt(8)
	v_mfma_f32_16x16x32_bf16 v[52:55], v[76:79], v[112:115], v[52:55]
	v_mfma_f32_16x16x32_bf16 v[8:11], v[80:83], v[112:115], v[8:11]
	ds_read_b128 v[92:95], v210 offset:24576
	s_waitcnt lgkmcnt(8)
	v_mfma_f32_16x16x32_bf16 v[56:59], v[76:79], v[116:119], v[56:59]
	v_mfma_f32_16x16x32_bf16 v[24:27], v[80:83], v[116:119], v[24:27]
	ds_read_b128 v[96:99], v210 offset:26624
	s_waitcnt lgkmcnt(8)
	v_mfma_f32_16x16x32_bf16 v[60:63], v[76:79], v[120:123], v[60:63]
	v_mfma_f32_16x16x32_bf16 v[28:31], v[80:83], v[120:123], v[28:31]
	ds_read_b128 v[100:103], v210 offset:28672
	s_waitcnt lgkmcnt(6)
	v_mfma_f32_16x16x32_bf16 v[32:35], v[84:87], v[124:127], v[32:35]
	v_mfma_f32_16x16x32_bf16 v[4:7], v[88:91], v[124:127], v[4:7]
	ds_read_b128 v[104:107], v210 offset:30720
	s_waitcnt vmcnt(0) lgkmcnt(0)
	s_barrier
	s_add_u32 m0, s88, 0
	s_nop 0
	global_load_lds_dwordx4 v212, s[84:85]
	s_waitcnt lgkmcnt(6)
	v_mfma_f32_16x16x32_bf16 v[36:39], v[84:87], v[140:143], v[36:39]
	v_mfma_f32_16x16x32_bf16 v[12:15], v[88:91], v[140:143], v[12:15]
	ds_read_b128 v[76:79], v204 offset:32768
	ds_read_b128 v[80:83], v204 offset:34816
	ds_read_b128 v[108:111], v208 offset:49152
	s_add_u32 m0, s88, 4096
	s_nop 0
	global_load_lds_dwordx4 v214, s[84:85]
	s_waitcnt lgkmcnt(8)
	v_mfma_f32_16x16x32_bf16 v[40:43], v[84:87], v[144:147], v[40:43]
	v_mfma_f32_16x16x32_bf16 v[16:19], v[88:91], v[144:147], v[16:19]
	ds_read_b128 v[112:115], v208 offset:51200
	s_add_u32 m0, s88, 8192
	s_nop 0
	global_load_lds_dwordx4 v216, s[84:85]
	s_waitcnt lgkmcnt(8)
	v_mfma_f32_16x16x32_bf16 v[44:47], v[84:87], v[148:151], v[44:47]
	v_mfma_f32_16x16x32_bf16 v[20:23], v[88:91], v[148:151], v[20:23]
	ds_read_b128 v[116:119], v208 offset:53248
	s_add_u32 m0, s88, 12288
	s_nop 0
	global_load_lds_dwordx4 v218, s[84:85]
	s_add_u32 s84, s84, 128
	s_addc_u32 s85, s85, 0
	s_waitcnt lgkmcnt(8)
	v_mfma_f32_16x16x32_bf16 v[48:51], v[84:87], v[92:95], v[48:51]
	v_mfma_f32_16x16x32_bf16 v[0:3], v[88:91], v[92:95], v[0:3]
	ds_read_b128 v[120:123], v208 offset:55296
	s_add_u32 m0, s88, 16384
	s_nop 0
	global_load_lds_dwordx4 v212, s[86:87]
	s_waitcnt lgkmcnt(8)
	v_mfma_f32_16x16x32_bf16 v[52:55], v[84:87], v[96:99], v[52:55]
	v_mfma_f32_16x16x32_bf16 v[8:11], v[88:91], v[96:99], v[8:11]
	ds_read_b128 v[124:127], v208 offset:57344
	s_add_u32 m0, s88, 20480
	s_nop 0
	global_load_lds_dwordx4 v214, s[86:87]
	s_waitcnt lgkmcnt(8)
	v_mfma_f32_16x16x32_bf16 v[56:59], v[84:87], v[100:103], v[56:59]
	v_mfma_f32_16x16x32_bf16 v[24:27], v[88:91], v[100:103], v[24:27]
	ds_read_b128 v[140:143], v208 offset:59392
	s_add_u32 m0, s88, 24576
	s_nop 0
	global_load_lds_dwordx4 v216, s[86:87]
	s_waitcnt lgkmcnt(8)
	v_mfma_f32_16x16x32_bf16 v[60:63], v[84:87], v[104:107], v[60:63]
	v_mfma_f32_16x16x32_bf16 v[28:31], v[88:91], v[104:107], v[28:31]
	ds_read_b128 v[144:147], v208 offset:61440
	s_add_u32 m0, s88, 28672
	s_nop 0
	global_load_lds_dwordx4 v218, s[86:87]
	s_add_u32 s86, s86, 128
	s_addc_u32 s87, s87, 0
	s_waitcnt lgkmcnt(6)
	v_mfma_f32_16x16x32_bf16 v[32:35], v[76:79], v[108:111], v[32:35]
	v_mfma_f32_16x16x32_bf16 v[4:7], v[80:83], v[108:111], v[4:7]
	ds_read_b128 v[148:151], v208 offset:63488
	s_waitcnt lgkmcnt(6)
	v_mfma_f32_16x16x32_bf16 v[36:39], v[76:79], v[112:115], v[36:39]
	v_mfma_f32_16x16x32_bf16 v[12:15], v[80:83], v[112:115], v[12:15]
	ds_read_b128 v[84:87], v206 offset:32768
	ds_read_b128 v[88:91], v206 offset:34816
	ds_read_b128 v[92:95], v210 offset:49152
	s_waitcnt lgkmcnt(8)
	v_mfma_f32_16x16x32_bf16 v[40:43], v[76:79], v[116:119], v[40:43]
	v_mfma_f32_16x16x32_bf16 v[16:19], v[80:83], v[116:119], v[16:19]
	ds_read_b128 v[96:99], v210 offset:51200
	s_waitcnt lgkmcnt(8)
	v_mfma_f32_16x16x32_bf16 v[44:47], v[76:79], v[120:123], v[44:47]
	v_mfma_f32_16x16x32_bf16 v[20:23], v[80:83], v[120:123], v[20:23]
	ds_read_b128 v[100:103], v210 offset:53248
	s_waitcnt lgkmcnt(8)
	v_mfma_f32_16x16x32_bf16 v[48:51], v[76:79], v[124:127], v[48:51]
	v_mfma_f32_16x16x32_bf16 v[0:3], v[80:83], v[124:127], v[0:3]
	ds_read_b128 v[104:107], v210 offset:55296
	s_waitcnt lgkmcnt(8)
	v_mfma_f32_16x16x32_bf16 v[52:55], v[76:79], v[140:143], v[52:55]
	v_mfma_f32_16x16x32_bf16 v[8:11], v[80:83], v[140:143], v[8:11]
	ds_read_b128 v[108:111], v210 offset:57344
	s_waitcnt lgkmcnt(8)
	v_mfma_f32_16x16x32_bf16 v[56:59], v[76:79], v[144:147], v[56:59]
	v_mfma_f32_16x16x32_bf16 v[24:27], v[80:83], v[144:147], v[24:27]
	ds_read_b128 v[112:115], v210 offset:59392
	s_waitcnt lgkmcnt(8)
	v_mfma_f32_16x16x32_bf16 v[60:63], v[76:79], v[148:151], v[60:63]
	v_mfma_f32_16x16x32_bf16 v[28:31], v[80:83], v[148:151], v[28:31]
	ds_read_b128 v[116:119], v210 offset:61440
	s_waitcnt lgkmcnt(6)
	v_mfma_f32_16x16x32_bf16 v[32:35], v[84:87], v[92:95], v[32:35]
	v_mfma_f32_16x16x32_bf16 v[4:7], v[88:91], v[92:95], v[4:7]
	ds_read_b128 v[120:123], v210 offset:63488
	s_waitcnt vmcnt(0) lgkmcnt(0)
	s_barrier
	s_add_u32 m0, s88, 32768
	s_nop 0
	global_load_lds_dwordx4 v212, s[84:85]
	s_waitcnt lgkmcnt(6)
	v_mfma_f32_16x16x32_bf16 v[36:39], v[84:87], v[96:99], v[36:39]
	v_mfma_f32_16x16x32_bf16 v[12:15], v[88:91], v[96:99], v[12:15]
	ds_read_b128 v[76:79], v204 offset:0
	ds_read_b128 v[80:83], v204 offset:2048
	ds_read_b128 v[124:127], v208 offset:16384
	s_add_u32 m0, s88, 36864
	s_nop 0
	global_load_lds_dwordx4 v214, s[84:85]
	s_waitcnt lgkmcnt(8)
	v_mfma_f32_16x16x32_bf16 v[40:43], v[84:87], v[100:103], v[40:43]
	v_mfma_f32_16x16x32_bf16 v[16:19], v[88:91], v[100:103], v[16:19]
	ds_read_b128 v[140:143], v208 offset:18432
	s_add_u32 m0, s88, 40960
	s_nop 0
	global_load_lds_dwordx4 v216, s[84:85]
	s_waitcnt lgkmcnt(8)
	v_mfma_f32_16x16x32_bf16 v[44:47], v[84:87], v[104:107], v[44:47]
	v_mfma_f32_16x16x32_bf16 v[20:23], v[88:91], v[104:107], v[20:23]
	ds_read_b128 v[144:147], v208 offset:20480
	s_add_u32 m0, s88, 45056
	s_nop 0
	global_load_lds_dwordx4 v218, s[84:85]
	s_add_u32 s84, s84, 128
	s_addc_u32 s85, s85, 0
	s_waitcnt lgkmcnt(8)
	v_mfma_f32_16x16x32_bf16 v[48:51], v[84:87], v[108:111], v[48:51]
	v_mfma_f32_16x16x32_bf16 v[0:3], v[88:91], v[108:111], v[0:3]
	ds_read_b128 v[148:151], v208 offset:22528
	s_add_u32 m0, s88, 49152
	s_nop 0
	global_load_lds_dwordx4 v212, s[86:87]
	s_waitcnt lgkmcnt(8)
	v_mfma_f32_16x16x32_bf16 v[52:55], v[84:87], v[112:115], v[52:55]
	v_mfma_f32_16x16x32_bf16 v[8:11], v[88:91], v[112:115], v[8:11]
	ds_read_b128 v[92:95], v208 offset:24576
	s_add_u32 m0, s88, 53248
	s_nop 0
	global_load_lds_dwordx4 v214, s[86:87]
	s_waitcnt lgkmcnt(8)
	v_mfma_f32_16x16x32_bf16 v[56:59], v[84:87], v[116:119], v[56:59]
	v_mfma_f32_16x16x32_bf16 v[24:27], v[88:91], v[116:119], v[24:27]
	ds_read_b128 v[96:99], v208 offset:26624
	s_add_u32 m0, s88, 57344
	s_nop 0
	global_load_lds_dwordx4 v216, s[86:87]
	s_waitcnt lgkmcnt(8)
	v_mfma_f32_16x16x32_bf16 v[60:63], v[84:87], v[120:123], v[60:63]
	v_mfma_f32_16x16x32_bf16 v[28:31], v[88:91], v[120:123], v[28:31]
	ds_read_b128 v[100:103], v208 offset:28672
	s_add_u32 m0, s88, 61440
	s_nop 0
	global_load_lds_dwordx4 v218, s[86:87]
	s_add_u32 s86, s86, 128
	s_addc_u32 s87, s87, 0
	s_waitcnt lgkmcnt(6)
	v_mfma_f32_16x16x32_bf16 v[32:35], v[76:79], v[124:127], v[32:35]
	v_mfma_f32_16x16x32_bf16 v[4:7], v[80:83], v[124:127], v[4:7]
	ds_read_b128 v[104:107], v208 offset:30720
	s_waitcnt lgkmcnt(6)
	v_mfma_f32_16x16x32_bf16 v[36:39], v[76:79], v[140:143], v[36:39]
	v_mfma_f32_16x16x32_bf16 v[12:15], v[80:83], v[140:143], v[12:15]
	ds_read_b128 v[84:87], v206 offset:0
	ds_read_b128 v[88:91], v206 offset:2048
	ds_read_b128 v[108:111], v210 offset:16384
	s_waitcnt lgkmcnt(8)
	v_mfma_f32_16x16x32_bf16 v[40:43], v[76:79], v[144:147], v[40:43]
	v_mfma_f32_16x16x32_bf16 v[16:19], v[80:83], v[144:147], v[16:19]
	ds_read_b128 v[112:115], v210 offset:18432
	s_waitcnt lgkmcnt(8)
	v_mfma_f32_16x16x32_bf16 v[44:47], v[76:79], v[148:151], v[44:47]
	v_mfma_f32_16x16x32_bf16 v[20:23], v[80:83], v[148:151], v[20:23]
	ds_read_b128 v[116:119], v210 offset:20480
	s_waitcnt lgkmcnt(8)
	v_mfma_f32_16x16x32_bf16 v[48:51], v[76:79], v[92:95], v[48:51]
	v_mfma_f32_16x16x32_bf16 v[0:3], v[80:83], v[92:95], v[0:3]
	ds_read_b128 v[120:123], v210 offset:22528
	s_waitcnt lgkmcnt(8)
	v_mfma_f32_16x16x32_bf16 v[52:55], v[76:79], v[96:99], v[52:55]
	v_mfma_f32_16x16x32_bf16 v[8:11], v[80:83], v[96:99], v[8:11]
	ds_read_b128 v[124:127], v210 offset:24576
	s_waitcnt lgkmcnt(8)
	v_mfma_f32_16x16x32_bf16 v[56:59], v[76:79], v[100:103], v[56:59]
	v_mfma_f32_16x16x32_bf16 v[24:27], v[80:83], v[100:103], v[24:27]
	ds_read_b128 v[140:143], v210 offset:26624
	s_waitcnt lgkmcnt(8)
	v_mfma_f32_16x16x32_bf16 v[60:63], v[76:79], v[104:107], v[60:63]
	v_mfma_f32_16x16x32_bf16 v[28:31], v[80:83], v[104:107], v[28:31]
	ds_read_b128 v[144:147], v210 offset:28672
	s_waitcnt lgkmcnt(6)
	v_mfma_f32_16x16x32_bf16 v[32:35], v[84:87], v[108:111], v[32:35]
	v_mfma_f32_16x16x32_bf16 v[4:7], v[88:91], v[108:111], v[4:7]
	ds_read_b128 v[148:151], v210 offset:30720
	s_waitcnt vmcnt(0) lgkmcnt(0)
	s_barrier
	s_add_u32 m0, s88, 0
	s_nop 0
	global_load_lds_dwordx4 v212, s[84:85]
	s_waitcnt lgkmcnt(6)
	v_mfma_f32_16x16x32_bf16 v[36:39], v[84:87], v[112:115], v[36:39]
	v_mfma_f32_16x16x32_bf16 v[12:15], v[88:91], v[112:115], v[12:15]
	ds_read_b128 v[76:79], v204 offset:32768
	ds_read_b128 v[80:83], v204 offset:34816
	ds_read_b128 v[92:95], v208 offset:49152
	s_add_u32 m0, s88, 4096
	s_nop 0
	global_load_lds_dwordx4 v214, s[84:85]
	s_waitcnt lgkmcnt(8)
	v_mfma_f32_16x16x32_bf16 v[40:43], v[84:87], v[116:119], v[40:43]
	v_mfma_f32_16x16x32_bf16 v[16:19], v[88:91], v[116:119], v[16:19]
	ds_read_b128 v[96:99], v208 offset:51200
	s_add_u32 m0, s88, 8192
	s_nop 0
	global_load_lds_dwordx4 v216, s[84:85]
	s_waitcnt lgkmcnt(8)
	v_mfma_f32_16x16x32_bf16 v[44:47], v[84:87], v[120:123], v[44:47]
	v_mfma_f32_16x16x32_bf16 v[20:23], v[88:91], v[120:123], v[20:23]
	ds_read_b128 v[100:103], v208 offset:53248
	s_add_u32 m0, s88, 12288
	s_nop 0
	global_load_lds_dwordx4 v218, s[84:85]
	s_add_u32 s84, s84, 128
	s_addc_u32 s85, s85, 0
	s_waitcnt lgkmcnt(8)
	v_mfma_f32_16x16x32_bf16 v[48:51], v[84:87], v[124:127], v[48:51]
	v_mfma_f32_16x16x32_bf16 v[0:3], v[88:91], v[124:127], v[0:3]
	ds_read_b128 v[104:107], v208 offset:55296
	s_add_u32 m0, s88, 16384
	s_nop 0
	global_load_lds_dwordx4 v212, s[86:87]
	s_waitcnt lgkmcnt(8)
	v_mfma_f32_16x16x32_bf16 v[52:55], v[84:87], v[140:143], v[52:55]
	v_mfma_f32_16x16x32_bf16 v[8:11], v[88:91], v[140:143], v[8:11]
	ds_read_b128 v[108:111], v208 offset:57344
	s_add_u32 m0, s88, 20480
	s_nop 0
	global_load_lds_dwordx4 v214, s[86:87]
	s_waitcnt lgkmcnt(8)
	v_mfma_f32_16x16x32_bf16 v[56:59], v[84:87], v[144:147], v[56:59]
	v_mfma_f32_16x16x32_bf16 v[24:27], v[88:91], v[144:147], v[24:27]
	ds_read_b128 v[112:115], v208 offset:59392
	s_add_u32 m0, s88, 24576
	s_nop 0
	global_load_lds_dwordx4 v216, s[86:87]
	s_waitcnt lgkmcnt(8)
	v_mfma_f32_16x16x32_bf16 v[60:63], v[84:87], v[148:151], v[60:63]
	v_mfma_f32_16x16x32_bf16 v[28:31], v[88:91], v[148:151], v[28:31]
	ds_read_b128 v[116:119], v208 offset:61440
	s_add_u32 m0, s88, 28672
	s_nop 0
	global_load_lds_dwordx4 v218, s[86:87]
	s_add_u32 s86, s86, 128
	s_addc_u32 s87, s87, 0
	s_waitcnt lgkmcnt(6)
	v_mfma_f32_16x16x32_bf16 v[32:35], v[76:79], v[92:95], v[32:35]
	v_mfma_f32_16x16x32_bf16 v[4:7], v[80:83], v[92:95], v[4:7]
	ds_read_b128 v[120:123], v208 offset:63488
	s_waitcnt lgkmcnt(6)
	v_mfma_f32_16x16x32_bf16 v[36:39], v[76:79], v[96:99], v[36:39]
	v_mfma_f32_16x16x32_bf16 v[12:15], v[80:83], v[96:99], v[12:15]
	ds_read_b128 v[84:87], v206 offset:32768
	ds_read_b128 v[88:91], v206 offset:34816
	ds_read_b128 v[124:127], v210 offset:49152
	s_waitcnt lgkmcnt(8)
	v_mfma_f32_16x16x32_bf16 v[40:43], v[76:79], v[100:103], v[40:43]
	v_mfma_f32_16x16x32_bf16 v[16:19], v[80:83], v[100:103], v[16:19]
	ds_read_b128 v[140:143], v210 offset:51200
	s_waitcnt lgkmcnt(8)
	v_mfma_f32_16x16x32_bf16 v[44:47], v[76:79], v[104:107], v[44:47]
	v_mfma_f32_16x16x32_bf16 v[20:23], v[80:83], v[104:107], v[20:23]
	ds_read_b128 v[144:147], v210 offset:53248
	s_waitcnt lgkmcnt(8)
	v_mfma_f32_16x16x32_bf16 v[48:51], v[76:79], v[108:111], v[48:51]
	v_mfma_f32_16x16x32_bf16 v[0:3], v[80:83], v[108:111], v[0:3]
	ds_read_b128 v[148:151], v210 offset:55296
	s_waitcnt lgkmcnt(8)
	v_mfma_f32_16x16x32_bf16 v[52:55], v[76:79], v[112:115], v[52:55]
	v_mfma_f32_16x16x32_bf16 v[8:11], v[80:83], v[112:115], v[8:11]
	ds_read_b128 v[92:95], v210 offset:57344
	s_waitcnt lgkmcnt(8)
	v_mfma_f32_16x16x32_bf16 v[56:59], v[76:79], v[116:119], v[56:59]
	v_mfma_f32_16x16x32_bf16 v[24:27], v[80:83], v[116:119], v[24:27]
	ds_read_b128 v[96:99], v210 offset:59392
	s_waitcnt lgkmcnt(8)
	v_mfma_f32_16x16x32_bf16 v[60:63], v[76:79], v[120:123], v[60:63]
	v_mfma_f32_16x16x32_bf16 v[28:31], v[80:83], v[120:123], v[28:31]
	ds_read_b128 v[100:103], v210 offset:61440
	s_waitcnt lgkmcnt(6)
	v_mfma_f32_16x16x32_bf16 v[32:35], v[84:87], v[124:127], v[32:35]
	v_mfma_f32_16x16x32_bf16 v[4:7], v[88:91], v[124:127], v[4:7]
	ds_read_b128 v[104:107], v210 offset:63488
	s_waitcnt vmcnt(0) lgkmcnt(0)
	s_barrier
	s_add_u32 m0, s88, 32768
	s_nop 0
	global_load_lds_dwordx4 v212, s[84:85]
	s_waitcnt lgkmcnt(6)
	v_mfma_f32_16x16x32_bf16 v[36:39], v[84:87], v[140:143], v[36:39]
	v_mfma_f32_16x16x32_bf16 v[12:15], v[88:91], v[140:143], v[12:15]
	ds_read_b128 v[76:79], v204 offset:0
	ds_read_b128 v[80:83], v204 offset:2048
	ds_read_b128 v[108:111], v208 offset:16384
	s_add_u32 m0, s88, 36864
	s_nop 0
	global_load_lds_dwordx4 v214, s[84:85]
	s_waitcnt lgkmcnt(8)
	v_mfma_f32_16x16x32_bf16 v[40:43], v[84:87], v[144:147], v[40:43]
	v_mfma_f32_16x16x32_bf16 v[16:19], v[88:91], v[144:147], v[16:19]
	ds_read_b128 v[112:115], v208 offset:18432
	s_add_u32 m0, s88, 40960
	s_nop 0
	global_load_lds_dwordx4 v216, s[84:85]
	s_waitcnt lgkmcnt(8)
	v_mfma_f32_16x16x32_bf16 v[44:47], v[84:87], v[148:151], v[44:47]
	v_mfma_f32_16x16x32_bf16 v[20:23], v[88:91], v[148:151], v[20:23]
	ds_read_b128 v[116:119], v208 offset:20480
	s_add_u32 m0, s88, 45056
	s_nop 0
	global_load_lds_dwordx4 v218, s[84:85]
	s_add_u32 s84, s84, 128
	s_addc_u32 s85, s85, 0
	s_waitcnt lgkmcnt(8)
	v_mfma_f32_16x16x32_bf16 v[48:51], v[84:87], v[92:95], v[48:51]
	v_mfma_f32_16x16x32_bf16 v[0:3], v[88:91], v[92:95], v[0:3]
	ds_read_b128 v[120:123], v208 offset:22528
	s_add_u32 m0, s88, 49152
	s_nop 0
	global_load_lds_dwordx4 v212, s[86:87]
	s_waitcnt lgkmcnt(8)
	v_mfma_f32_16x16x32_bf16 v[52:55], v[84:87], v[96:99], v[52:55]
	v_mfma_f32_16x16x32_bf16 v[8:11], v[88:91], v[96:99], v[8:11]
	ds_read_b128 v[124:127], v208 offset:24576
	s_add_u32 m0, s88, 53248
	s_nop 0
	global_load_lds_dwordx4 v214, s[86:87]
	s_waitcnt lgkmcnt(8)
	v_mfma_f32_16x16x32_bf16 v[56:59], v[84:87], v[100:103], v[56:59]
	v_mfma_f32_16x16x32_bf16 v[24:27], v[88:91], v[100:103], v[24:27]
	ds_read_b128 v[140:143], v208 offset:26624
	s_add_u32 m0, s88, 57344
	s_nop 0
	global_load_lds_dwordx4 v216, s[86:87]
	s_waitcnt lgkmcnt(8)
	v_mfma_f32_16x16x32_bf16 v[60:63], v[84:87], v[104:107], v[60:63]
	v_mfma_f32_16x16x32_bf16 v[28:31], v[88:91], v[104:107], v[28:31]
	ds_read_b128 v[144:147], v208 offset:28672
	s_add_u32 m0, s88, 61440
	s_nop 0
	global_load_lds_dwordx4 v218, s[86:87]
	s_add_u32 s86, s86, 128
	s_addc_u32 s87, s87, 0
	s_waitcnt lgkmcnt(6)
	v_mfma_f32_16x16x32_bf16 v[32:35], v[76:79], v[108:111], v[32:35]
	v_mfma_f32_16x16x32_bf16 v[4:7], v[80:83], v[108:111], v[4:7]
	ds_read_b128 v[148:151], v208 offset:30720
	s_waitcnt lgkmcnt(6)
	v_mfma_f32_16x16x32_bf16 v[36:39], v[76:79], v[112:115], v[36:39]
	v_mfma_f32_16x16x32_bf16 v[12:15], v[80:83], v[112:115], v[12:15]
	ds_read_b128 v[84:87], v206 offset:0
	ds_read_b128 v[88:91], v206 offset:2048
	ds_read_b128 v[92:95], v210 offset:16384
	s_waitcnt lgkmcnt(8)
	v_mfma_f32_16x16x32_bf16 v[40:43], v[76:79], v[116:119], v[40:43]
	v_mfma_f32_16x16x32_bf16 v[16:19], v[80:83], v[116:119], v[16:19]
	ds_read_b128 v[96:99], v210 offset:18432
	s_waitcnt lgkmcnt(8)
	v_mfma_f32_16x16x32_bf16 v[44:47], v[76:79], v[120:123], v[44:47]
	v_mfma_f32_16x16x32_bf16 v[20:23], v[80:83], v[120:123], v[20:23]
	ds_read_b128 v[100:103], v210 offset:20480
	s_waitcnt lgkmcnt(8)
	v_mfma_f32_16x16x32_bf16 v[48:51], v[76:79], v[124:127], v[48:51]
	v_mfma_f32_16x16x32_bf16 v[0:3], v[80:83], v[124:127], v[0:3]
	ds_read_b128 v[104:107], v210 offset:22528
	s_waitcnt lgkmcnt(8)
	v_mfma_f32_16x16x32_bf16 v[52:55], v[76:79], v[140:143], v[52:55]
	v_mfma_f32_16x16x32_bf16 v[8:11], v[80:83], v[140:143], v[8:11]
	ds_read_b128 v[108:111], v210 offset:24576
	s_waitcnt lgkmcnt(8)
	v_mfma_f32_16x16x32_bf16 v[56:59], v[76:79], v[144:147], v[56:59]
	v_mfma_f32_16x16x32_bf16 v[24:27], v[80:83], v[144:147], v[24:27]
	ds_read_b128 v[112:115], v210 offset:26624
	s_waitcnt lgkmcnt(8)
	v_mfma_f32_16x16x32_bf16 v[60:63], v[76:79], v[148:151], v[60:63]
	v_mfma_f32_16x16x32_bf16 v[28:31], v[80:83], v[148:151], v[28:31]
	ds_read_b128 v[116:119], v210 offset:28672
	s_waitcnt lgkmcnt(6)
	v_mfma_f32_16x16x32_bf16 v[32:35], v[84:87], v[92:95], v[32:35]
	v_mfma_f32_16x16x32_bf16 v[4:7], v[88:91], v[92:95], v[4:7]
	ds_read_b128 v[120:123], v210 offset:30720
	s_waitcnt vmcnt(0) lgkmcnt(0)
	s_barrier
	s_add_u32 m0, s88, 0
	s_nop 0
	global_load_lds_dwordx4 v212, s[84:85]
	s_waitcnt lgkmcnt(6)
	v_mfma_f32_16x16x32_bf16 v[36:39], v[84:87], v[96:99], v[36:39]
	v_mfma_f32_16x16x32_bf16 v[12:15], v[88:91], v[96:99], v[12:15]
	ds_read_b128 v[76:79], v204 offset:32768
	ds_read_b128 v[80:83], v204 offset:34816
	ds_read_b128 v[124:127], v208 offset:49152
	s_add_u32 m0, s88, 4096
	s_nop 0
	global_load_lds_dwordx4 v214, s[84:85]
	s_waitcnt lgkmcnt(8)
	v_mfma_f32_16x16x32_bf16 v[40:43], v[84:87], v[100:103], v[40:43]
	v_mfma_f32_16x16x32_bf16 v[16:19], v[88:91], v[100:103], v[16:19]
	ds_read_b128 v[140:143], v208 offset:51200
	s_add_u32 m0, s88, 8192
	s_nop 0
	global_load_lds_dwordx4 v216, s[84:85]
	s_waitcnt lgkmcnt(8)
	v_mfma_f32_16x16x32_bf16 v[44:47], v[84:87], v[104:107], v[44:47]
	v_mfma_f32_16x16x32_bf16 v[20:23], v[88:91], v[104:107], v[20:23]
	ds_read_b128 v[144:147], v208 offset:53248
	s_add_u32 m0, s88, 12288
	s_nop 0
	global_load_lds_dwordx4 v218, s[84:85]
	s_add_u32 s84, s84, 128
	s_addc_u32 s85, s85, 0
	s_waitcnt lgkmcnt(8)
	v_mfma_f32_16x16x32_bf16 v[48:51], v[84:87], v[108:111], v[48:51]
	v_mfma_f32_16x16x32_bf16 v[0:3], v[88:91], v[108:111], v[0:3]
	ds_read_b128 v[148:151], v208 offset:55296
	s_add_u32 m0, s88, 16384
	s_nop 0
	global_load_lds_dwordx4 v212, s[86:87]
	s_waitcnt lgkmcnt(8)
	v_mfma_f32_16x16x32_bf16 v[52:55], v[84:87], v[112:115], v[52:55]
	v_mfma_f32_16x16x32_bf16 v[8:11], v[88:91], v[112:115], v[8:11]
	ds_read_b128 v[92:95], v208 offset:57344
	s_add_u32 m0, s88, 20480
	s_nop 0
	global_load_lds_dwordx4 v214, s[86:87]
	s_waitcnt lgkmcnt(8)
	v_mfma_f32_16x16x32_bf16 v[56:59], v[84:87], v[116:119], v[56:59]
	v_mfma_f32_16x16x32_bf16 v[24:27], v[88:91], v[116:119], v[24:27]
	ds_read_b128 v[96:99], v208 offset:59392
	s_add_u32 m0, s88, 24576
	s_nop 0
	global_load_lds_dwordx4 v216, s[86:87]
	s_waitcnt lgkmcnt(8)
	v_mfma_f32_16x16x32_bf16 v[60:63], v[84:87], v[120:123], v[60:63]
	v_mfma_f32_16x16x32_bf16 v[28:31], v[88:91], v[120:123], v[28:31]
	ds_read_b128 v[100:103], v208 offset:61440
	s_add_u32 m0, s88, 28672
	s_nop 0
	global_load_lds_dwordx4 v218, s[86:87]
	s_add_u32 s86, s86, 128
	s_addc_u32 s87, s87, 0
	s_waitcnt lgkmcnt(6)
	v_mfma_f32_16x16x32_bf16 v[32:35], v[76:79], v[124:127], v[32:35]
	v_mfma_f32_16x16x32_bf16 v[4:7], v[80:83], v[124:127], v[4:7]
	ds_read_b128 v[104:107], v208 offset:63488
	s_waitcnt lgkmcnt(6)
	v_mfma_f32_16x16x32_bf16 v[36:39], v[76:79], v[140:143], v[36:39]
	v_mfma_f32_16x16x32_bf16 v[12:15], v[80:83], v[140:143], v[12:15]
	ds_read_b128 v[84:87], v206 offset:32768
	ds_read_b128 v[88:91], v206 offset:34816
	ds_read_b128 v[108:111], v210 offset:49152
	s_waitcnt lgkmcnt(8)
	v_mfma_f32_16x16x32_bf16 v[40:43], v[76:79], v[144:147], v[40:43]
	v_mfma_f32_16x16x32_bf16 v[16:19], v[80:83], v[144:147], v[16:19]
	ds_read_b128 v[112:115], v210 offset:51200
	s_waitcnt lgkmcnt(8)
	v_mfma_f32_16x16x32_bf16 v[44:47], v[76:79], v[148:151], v[44:47]
	v_mfma_f32_16x16x32_bf16 v[20:23], v[80:83], v[148:151], v[20:23]
	ds_read_b128 v[116:119], v210 offset:53248
	s_waitcnt lgkmcnt(8)
	v_mfma_f32_16x16x32_bf16 v[48:51], v[76:79], v[92:95], v[48:51]
	v_mfma_f32_16x16x32_bf16 v[0:3], v[80:83], v[92:95], v[0:3]
	ds_read_b128 v[120:123], v210 offset:55296
	s_waitcnt lgkmcnt(8)
	v_mfma_f32_16x16x32_bf16 v[52:55], v[76:79], v[96:99], v[52:55]
	v_mfma_f32_16x16x32_bf16 v[8:11], v[80:83], v[96:99], v[8:11]
	ds_read_b128 v[124:127], v210 offset:57344
	s_waitcnt lgkmcnt(8)
	v_mfma_f32_16x16x32_bf16 v[56:59], v[76:79], v[100:103], v[56:59]
	v_mfma_f32_16x16x32_bf16 v[24:27], v[80:83], v[100:103], v[24:27]
	ds_read_b128 v[140:143], v210 offset:59392
	s_waitcnt lgkmcnt(8)
	v_mfma_f32_16x16x32_bf16 v[60:63], v[76:79], v[104:107], v[60:63]
	v_mfma_f32_16x16x32_bf16 v[28:31], v[80:83], v[104:107], v[28:31]
	ds_read_b128 v[144:147], v210 offset:61440
	s_waitcnt lgkmcnt(6)
	v_mfma_f32_16x16x32_bf16 v[32:35], v[84:87], v[108:111], v[32:35]
	v_mfma_f32_16x16x32_bf16 v[4:7], v[88:91], v[108:111], v[4:7]
	ds_read_b128 v[148:151], v210 offset:63488
	s_waitcnt vmcnt(0) lgkmcnt(0)
	s_barrier
	s_add_u32 m0, s88, 32768
	s_nop 0
	global_load_lds_dwordx4 v212, s[84:85]
	s_waitcnt lgkmcnt(6)
	v_mfma_f32_16x16x32_bf16 v[36:39], v[84:87], v[112:115], v[36:39]
	v_mfma_f32_16x16x32_bf16 v[12:15], v[88:91], v[112:115], v[12:15]
	ds_read_b128 v[76:79], v204 offset:0
	ds_read_b128 v[80:83], v204 offset:2048
	ds_read_b128 v[92:95], v208 offset:16384
	s_add_u32 m0, s88, 36864
	s_nop 0
	global_load_lds_dwordx4 v214, s[84:85]
	s_waitcnt lgkmcnt(8)
	v_mfma_f32_16x16x32_bf16 v[40:43], v[84:87], v[116:119], v[40:43]
	v_mfma_f32_16x16x32_bf16 v[16:19], v[88:91], v[116:119], v[16:19]
	ds_read_b128 v[96:99], v208 offset:18432
	s_add_u32 m0, s88, 40960
	s_nop 0
	global_load_lds_dwordx4 v216, s[84:85]
	s_waitcnt lgkmcnt(8)
	v_mfma_f32_16x16x32_bf16 v[44:47], v[84:87], v[120:123], v[44:47]
	v_mfma_f32_16x16x32_bf16 v[20:23], v[88:91], v[120:123], v[20:23]
	ds_read_b128 v[100:103], v208 offset:20480
	s_add_u32 m0, s88, 45056
	s_nop 0
	global_load_lds_dwordx4 v218, s[84:85]
	s_add_u32 s84, s84, 128
	s_addc_u32 s85, s85, 0
	s_waitcnt lgkmcnt(8)
	v_mfma_f32_16x16x32_bf16 v[48:51], v[84:87], v[124:127], v[48:51]
	v_mfma_f32_16x16x32_bf16 v[0:3], v[88:91], v[124:127], v[0:3]
	ds_read_b128 v[104:107], v208 offset:22528
	s_add_u32 m0, s88, 49152
	s_nop 0
	global_load_lds_dwordx4 v212, s[86:87]
	s_waitcnt lgkmcnt(8)
	v_mfma_f32_16x16x32_bf16 v[52:55], v[84:87], v[140:143], v[52:55]
	v_mfma_f32_16x16x32_bf16 v[8:11], v[88:91], v[140:143], v[8:11]
	ds_read_b128 v[108:111], v208 offset:24576
	s_add_u32 m0, s88, 53248
	s_nop 0
	global_load_lds_dwordx4 v214, s[86:87]
	s_waitcnt lgkmcnt(8)
	v_mfma_f32_16x16x32_bf16 v[56:59], v[84:87], v[144:147], v[56:59]
	v_mfma_f32_16x16x32_bf16 v[24:27], v[88:91], v[144:147], v[24:27]
	ds_read_b128 v[112:115], v208 offset:26624
	s_add_u32 m0, s88, 57344
	s_nop 0
	global_load_lds_dwordx4 v216, s[86:87]
	s_waitcnt lgkmcnt(8)
	v_mfma_f32_16x16x32_bf16 v[60:63], v[84:87], v[148:151], v[60:63]
	v_mfma_f32_16x16x32_bf16 v[28:31], v[88:91], v[148:151], v[28:31]
	ds_read_b128 v[116:119], v208 offset:28672
	s_add_u32 m0, s88, 61440
	s_nop 0
	global_load_lds_dwordx4 v218, s[86:87]
	s_add_u32 s86, s86, 128
	s_addc_u32 s87, s87, 0
	s_waitcnt lgkmcnt(6)
	v_mfma_f32_16x16x32_bf16 v[32:35], v[76:79], v[92:95], v[32:35]
	v_mfma_f32_16x16x32_bf16 v[4:7], v[80:83], v[92:95], v[4:7]
	ds_read_b128 v[120:123], v208 offset:30720
	s_waitcnt lgkmcnt(6)
	v_mfma_f32_16x16x32_bf16 v[36:39], v[76:79], v[96:99], v[36:39]
	v_mfma_f32_16x16x32_bf16 v[12:15], v[80:83], v[96:99], v[12:15]
	ds_read_b128 v[84:87], v206 offset:0
	ds_read_b128 v[88:91], v206 offset:2048
	ds_read_b128 v[124:127], v210 offset:16384
	s_waitcnt lgkmcnt(8)
	v_mfma_f32_16x16x32_bf16 v[40:43], v[76:79], v[100:103], v[40:43]
	v_mfma_f32_16x16x32_bf16 v[16:19], v[80:83], v[100:103], v[16:19]
	ds_read_b128 v[140:143], v210 offset:18432
	s_waitcnt lgkmcnt(8)
	v_mfma_f32_16x16x32_bf16 v[44:47], v[76:79], v[104:107], v[44:47]
	v_mfma_f32_16x16x32_bf16 v[20:23], v[80:83], v[104:107], v[20:23]
	ds_read_b128 v[144:147], v210 offset:20480
	s_waitcnt lgkmcnt(8)
	v_mfma_f32_16x16x32_bf16 v[48:51], v[76:79], v[108:111], v[48:51]
	v_mfma_f32_16x16x32_bf16 v[0:3], v[80:83], v[108:111], v[0:3]
	ds_read_b128 v[148:151], v210 offset:22528
	s_waitcnt lgkmcnt(8)
	v_mfma_f32_16x16x32_bf16 v[52:55], v[76:79], v[112:115], v[52:55]
	v_mfma_f32_16x16x32_bf16 v[8:11], v[80:83], v[112:115], v[8:11]
	ds_read_b128 v[92:95], v210 offset:24576
	s_waitcnt lgkmcnt(8)
	v_mfma_f32_16x16x32_bf16 v[56:59], v[76:79], v[116:119], v[56:59]
	v_mfma_f32_16x16x32_bf16 v[24:27], v[80:83], v[116:119], v[24:27]
	ds_read_b128 v[96:99], v210 offset:26624
	s_waitcnt lgkmcnt(8)
	v_mfma_f32_16x16x32_bf16 v[60:63], v[76:79], v[120:123], v[60:63]
	v_mfma_f32_16x16x32_bf16 v[28:31], v[80:83], v[120:123], v[28:31]
	ds_read_b128 v[100:103], v210 offset:28672
	s_waitcnt lgkmcnt(6)
	v_mfma_f32_16x16x32_bf16 v[32:35], v[84:87], v[124:127], v[32:35]
	v_mfma_f32_16x16x32_bf16 v[4:7], v[88:91], v[124:127], v[4:7]
	ds_read_b128 v[104:107], v210 offset:30720
	s_waitcnt vmcnt(0) lgkmcnt(0)
	s_barrier
	s_add_u32 m0, s88, 0
	s_nop 0
	global_load_lds_dwordx4 v212, s[84:85]
	s_waitcnt lgkmcnt(6)
	v_mfma_f32_16x16x32_bf16 v[36:39], v[84:87], v[140:143], v[36:39]
	v_mfma_f32_16x16x32_bf16 v[12:15], v[88:91], v[140:143], v[12:15]
	ds_read_b128 v[76:79], v204 offset:32768
	ds_read_b128 v[80:83], v204 offset:34816
	ds_read_b128 v[108:111], v208 offset:49152
	s_add_u32 m0, s88, 4096
	s_nop 0
	global_load_lds_dwordx4 v214, s[84:85]
	s_waitcnt lgkmcnt(8)
	v_mfma_f32_16x16x32_bf16 v[40:43], v[84:87], v[144:147], v[40:43]
	v_mfma_f32_16x16x32_bf16 v[16:19], v[88:91], v[144:147], v[16:19]
	ds_read_b128 v[112:115], v208 offset:51200
	s_add_u32 m0, s88, 8192
	s_nop 0
	global_load_lds_dwordx4 v216, s[84:85]
	s_waitcnt lgkmcnt(8)
	v_mfma_f32_16x16x32_bf16 v[44:47], v[84:87], v[148:151], v[44:47]
	v_mfma_f32_16x16x32_bf16 v[20:23], v[88:91], v[148:151], v[20:23]
	ds_read_b128 v[116:119], v208 offset:53248
	s_add_u32 m0, s88, 12288
	s_nop 0
	global_load_lds_dwordx4 v218, s[84:85]
	s_add_u32 s84, s84, 128
	s_addc_u32 s85, s85, 0
	s_waitcnt lgkmcnt(8)
	v_mfma_f32_16x16x32_bf16 v[48:51], v[84:87], v[92:95], v[48:51]
	v_mfma_f32_16x16x32_bf16 v[0:3], v[88:91], v[92:95], v[0:3]
	ds_read_b128 v[120:123], v208 offset:55296
	s_add_u32 m0, s88, 16384
	s_nop 0
	global_load_lds_dwordx4 v212, s[86:87]
	s_waitcnt lgkmcnt(8)
	v_mfma_f32_16x16x32_bf16 v[52:55], v[84:87], v[96:99], v[52:55]
	v_mfma_f32_16x16x32_bf16 v[8:11], v[88:91], v[96:99], v[8:11]
	ds_read_b128 v[124:127], v208 offset:57344
	s_add_u32 m0, s88, 20480
	s_nop 0
	global_load_lds_dwordx4 v214, s[86:87]
	s_waitcnt lgkmcnt(8)
	v_mfma_f32_16x16x32_bf16 v[56:59], v[84:87], v[100:103], v[56:59]
	v_mfma_f32_16x16x32_bf16 v[24:27], v[88:91], v[100:103], v[24:27]
	ds_read_b128 v[140:143], v208 offset:59392
	s_add_u32 m0, s88, 24576
	s_nop 0
	global_load_lds_dwordx4 v216, s[86:87]
	s_waitcnt lgkmcnt(8)
	v_mfma_f32_16x16x32_bf16 v[60:63], v[84:87], v[104:107], v[60:63]
	v_mfma_f32_16x16x32_bf16 v[28:31], v[88:91], v[104:107], v[28:31]
	ds_read_b128 v[144:147], v208 offset:61440
	s_add_u32 m0, s88, 28672
	s_nop 0
	global_load_lds_dwordx4 v218, s[86:87]
	s_add_u32 s86, s86, 128
	s_addc_u32 s87, s87, 0
	s_waitcnt lgkmcnt(6)
	v_mfma_f32_16x16x32_bf16 v[32:35], v[76:79], v[108:111], v[32:35]
	v_mfma_f32_16x16x32_bf16 v[4:7], v[80:83], v[108:111], v[4:7]
	ds_read_b128 v[148:151], v208 offset:63488
	s_waitcnt lgkmcnt(6)
	v_mfma_f32_16x16x32_bf16 v[36:39], v[76:79], v[112:115], v[36:39]
	v_mfma_f32_16x16x32_bf16 v[12:15], v[80:83], v[112:115], v[12:15]
	ds_read_b128 v[84:87], v206 offset:32768
	ds_read_b128 v[88:91], v206 offset:34816
	ds_read_b128 v[92:95], v210 offset:49152
	s_waitcnt lgkmcnt(8)
	v_mfma_f32_16x16x32_bf16 v[40:43], v[76:79], v[116:119], v[40:43]
	v_mfma_f32_16x16x32_bf16 v[16:19], v[80:83], v[116:119], v[16:19]
	ds_read_b128 v[96:99], v210 offset:51200
	s_waitcnt lgkmcnt(8)
	v_mfma_f32_16x16x32_bf16 v[44:47], v[76:79], v[120:123], v[44:47]
	v_mfma_f32_16x16x32_bf16 v[20:23], v[80:83], v[120:123], v[20:23]
	ds_read_b128 v[100:103], v210 offset:53248
	s_waitcnt lgkmcnt(8)
	v_mfma_f32_16x16x32_bf16 v[48:51], v[76:79], v[124:127], v[48:51]
	v_mfma_f32_16x16x32_bf16 v[0:3], v[80:83], v[124:127], v[0:3]
	ds_read_b128 v[104:107], v210 offset:55296
	s_waitcnt lgkmcnt(8)
	v_mfma_f32_16x16x32_bf16 v[52:55], v[76:79], v[140:143], v[52:55]
	v_mfma_f32_16x16x32_bf16 v[8:11], v[80:83], v[140:143], v[8:11]
	ds_read_b128 v[108:111], v210 offset:57344
	s_waitcnt lgkmcnt(8)
	v_mfma_f32_16x16x32_bf16 v[56:59], v[76:79], v[144:147], v[56:59]
	v_mfma_f32_16x16x32_bf16 v[24:27], v[80:83], v[144:147], v[24:27]
	ds_read_b128 v[112:115], v210 offset:59392
	s_waitcnt lgkmcnt(8)
	v_mfma_f32_16x16x32_bf16 v[60:63], v[76:79], v[148:151], v[60:63]
	v_mfma_f32_16x16x32_bf16 v[28:31], v[80:83], v[148:151], v[28:31]
	ds_read_b128 v[116:119], v210 offset:61440
	s_waitcnt lgkmcnt(6)
	v_mfma_f32_16x16x32_bf16 v[32:35], v[84:87], v[92:95], v[32:35]
	v_mfma_f32_16x16x32_bf16 v[4:7], v[88:91], v[92:95], v[4:7]
	ds_read_b128 v[120:123], v210 offset:63488
	s_waitcnt vmcnt(0) lgkmcnt(0)
	s_barrier
	s_add_u32 m0, s88, 32768
	s_nop 0
	global_load_lds_dwordx4 v212, s[84:85]
	s_waitcnt lgkmcnt(6)
	v_mfma_f32_16x16x32_bf16 v[36:39], v[84:87], v[96:99], v[36:39]
	v_mfma_f32_16x16x32_bf16 v[12:15], v[88:91], v[96:99], v[12:15]
	ds_read_b128 v[76:79], v204 offset:0
	ds_read_b128 v[80:83], v204 offset:2048
	ds_read_b128 v[124:127], v208 offset:16384
	s_add_u32 m0, s88, 36864
	s_nop 0
	global_load_lds_dwordx4 v214, s[84:85]
	s_waitcnt lgkmcnt(8)
	v_mfma_f32_16x16x32_bf16 v[40:43], v[84:87], v[100:103], v[40:43]
	v_mfma_f32_16x16x32_bf16 v[16:19], v[88:91], v[100:103], v[16:19]
	ds_read_b128 v[140:143], v208 offset:18432
	s_add_u32 m0, s88, 40960
	s_nop 0
	global_load_lds_dwordx4 v216, s[84:85]
	s_waitcnt lgkmcnt(8)
	v_mfma_f32_16x16x32_bf16 v[44:47], v[84:87], v[104:107], v[44:47]
	v_mfma_f32_16x16x32_bf16 v[20:23], v[88:91], v[104:107], v[20:23]
	ds_read_b128 v[144:147], v208 offset:20480
	s_add_u32 m0, s88, 45056
	s_nop 0
	global_load_lds_dwordx4 v218, s[84:85]
	s_add_u32 s84, s84, 128
	s_addc_u32 s85, s85, 0
	s_waitcnt lgkmcnt(8)
	v_mfma_f32_16x16x32_bf16 v[48:51], v[84:87], v[108:111], v[48:51]
	v_mfma_f32_16x16x32_bf16 v[0:3], v[88:91], v[108:111], v[0:3]
	ds_read_b128 v[148:151], v208 offset:22528
	s_add_u32 m0, s88, 49152
	s_nop 0
	global_load_lds_dwordx4 v212, s[86:87]
	s_waitcnt lgkmcnt(8)
	v_mfma_f32_16x16x32_bf16 v[52:55], v[84:87], v[112:115], v[52:55]
	v_mfma_f32_16x16x32_bf16 v[8:11], v[88:91], v[112:115], v[8:11]
	ds_read_b128 v[92:95], v208 offset:24576
	s_add_u32 m0, s88, 53248
	s_nop 0
	global_load_lds_dwordx4 v214, s[86:87]
	s_waitcnt lgkmcnt(8)
	v_mfma_f32_16x16x32_bf16 v[56:59], v[84:87], v[116:119], v[56:59]
	v_mfma_f32_16x16x32_bf16 v[24:27], v[88:91], v[116:119], v[24:27]
	ds_read_b128 v[96:99], v208 offset:26624
	s_add_u32 m0, s88, 57344
	s_nop 0
	global_load_lds_dwordx4 v216, s[86:87]
	s_waitcnt lgkmcnt(8)
	v_mfma_f32_16x16x32_bf16 v[60:63], v[84:87], v[120:123], v[60:63]
	v_mfma_f32_16x16x32_bf16 v[28:31], v[88:91], v[120:123], v[28:31]
	ds_read_b128 v[100:103], v208 offset:28672
	s_add_u32 m0, s88, 61440
	s_nop 0
	global_load_lds_dwordx4 v218, s[86:87]
	s_add_u32 s86, s86, 128
	s_addc_u32 s87, s87, 0
	s_waitcnt lgkmcnt(6)
	v_mfma_f32_16x16x32_bf16 v[32:35], v[76:79], v[124:127], v[32:35]
	v_mfma_f32_16x16x32_bf16 v[4:7], v[80:83], v[124:127], v[4:7]
	ds_read_b128 v[104:107], v208 offset:30720
	s_waitcnt lgkmcnt(6)
	v_mfma_f32_16x16x32_bf16 v[36:39], v[76:79], v[140:143], v[36:39]
	v_mfma_f32_16x16x32_bf16 v[12:15], v[80:83], v[140:143], v[12:15]
	ds_read_b128 v[84:87], v206 offset:0
	ds_read_b128 v[88:91], v206 offset:2048
	ds_read_b128 v[108:111], v210 offset:16384
	s_waitcnt lgkmcnt(8)
	v_mfma_f32_16x16x32_bf16 v[40:43], v[76:79], v[144:147], v[40:43]
	v_mfma_f32_16x16x32_bf16 v[16:19], v[80:83], v[144:147], v[16:19]
	ds_read_b128 v[112:115], v210 offset:18432
	s_waitcnt lgkmcnt(8)
	v_mfma_f32_16x16x32_bf16 v[44:47], v[76:79], v[148:151], v[44:47]
	v_mfma_f32_16x16x32_bf16 v[20:23], v[80:83], v[148:151], v[20:23]
	ds_read_b128 v[116:119], v210 offset:20480
	s_waitcnt lgkmcnt(8)
	v_mfma_f32_16x16x32_bf16 v[48:51], v[76:79], v[92:95], v[48:51]
	v_mfma_f32_16x16x32_bf16 v[0:3], v[80:83], v[92:95], v[0:3]
	ds_read_b128 v[120:123], v210 offset:22528
	s_waitcnt lgkmcnt(8)
	v_mfma_f32_16x16x32_bf16 v[52:55], v[76:79], v[96:99], v[52:55]
	v_mfma_f32_16x16x32_bf16 v[8:11], v[80:83], v[96:99], v[8:11]
	ds_read_b128 v[124:127], v210 offset:24576
	s_waitcnt lgkmcnt(8)
	v_mfma_f32_16x16x32_bf16 v[56:59], v[76:79], v[100:103], v[56:59]
	v_mfma_f32_16x16x32_bf16 v[24:27], v[80:83], v[100:103], v[24:27]
	ds_read_b128 v[140:143], v210 offset:26624
	s_waitcnt lgkmcnt(8)
	v_mfma_f32_16x16x32_bf16 v[60:63], v[76:79], v[104:107], v[60:63]
	v_mfma_f32_16x16x32_bf16 v[28:31], v[80:83], v[104:107], v[28:31]
	ds_read_b128 v[144:147], v210 offset:28672
	s_waitcnt lgkmcnt(6)
	v_mfma_f32_16x16x32_bf16 v[32:35], v[84:87], v[108:111], v[32:35]
	v_mfma_f32_16x16x32_bf16 v[4:7], v[88:91], v[108:111], v[4:7]
	ds_read_b128 v[148:151], v210 offset:30720
	s_waitcnt vmcnt(0) lgkmcnt(0)
	s_barrier
	s_waitcnt lgkmcnt(6)
	v_mfma_f32_16x16x32_bf16 v[36:39], v[84:87], v[112:115], v[36:39]
	v_mfma_f32_16x16x32_bf16 v[12:15], v[88:91], v[112:115], v[12:15]
	ds_read_b128 v[76:79], v204 offset:32768
	ds_read_b128 v[80:83], v204 offset:34816
	ds_read_b128 v[92:95], v208 offset:49152
	s_waitcnt lgkmcnt(8)
	v_mfma_f32_16x16x32_bf16 v[40:43], v[84:87], v[116:119], v[40:43]
	v_mfma_f32_16x16x32_bf16 v[16:19], v[88:91], v[116:119], v[16:19]
	ds_read_b128 v[96:99], v208 offset:51200
	s_waitcnt lgkmcnt(8)
	v_mfma_f32_16x16x32_bf16 v[44:47], v[84:87], v[120:123], v[44:47]
	v_mfma_f32_16x16x32_bf16 v[20:23], v[88:91], v[120:123], v[20:23]
	ds_read_b128 v[100:103], v208 offset:53248
	s_waitcnt lgkmcnt(8)
	v_mfma_f32_16x16x32_bf16 v[48:51], v[84:87], v[124:127], v[48:51]
	v_mfma_f32_16x16x32_bf16 v[0:3], v[88:91], v[124:127], v[0:3]
	ds_read_b128 v[104:107], v208 offset:55296
	s_waitcnt lgkmcnt(8)
	v_mfma_f32_16x16x32_bf16 v[52:55], v[84:87], v[140:143], v[52:55]
	v_mfma_f32_16x16x32_bf16 v[8:11], v[88:91], v[140:143], v[8:11]
	ds_read_b128 v[108:111], v208 offset:57344
	s_waitcnt lgkmcnt(8)
	v_mfma_f32_16x16x32_bf16 v[56:59], v[84:87], v[144:147], v[56:59]
	v_mfma_f32_16x16x32_bf16 v[24:27], v[88:91], v[144:147], v[24:27]
	ds_read_b128 v[112:115], v208 offset:59392
	s_waitcnt lgkmcnt(8)
	v_mfma_f32_16x16x32_bf16 v[60:63], v[84:87], v[148:151], v[60:63]
	v_mfma_f32_16x16x32_bf16 v[28:31], v[88:91], v[148:151], v[28:31]
	ds_read_b128 v[116:119], v208 offset:61440
	s_waitcnt lgkmcnt(6)
	v_mfma_f32_16x16x32_bf16 v[32:35], v[76:79], v[92:95], v[32:35]
	v_mfma_f32_16x16x32_bf16 v[4:7], v[80:83], v[92:95], v[4:7]
	ds_read_b128 v[120:123], v208 offset:63488
	s_waitcnt lgkmcnt(6)
	v_mfma_f32_16x16x32_bf16 v[36:39], v[76:79], v[96:99], v[36:39]
	v_mfma_f32_16x16x32_bf16 v[12:15], v[80:83], v[96:99], v[12:15]
	ds_read_b128 v[84:87], v206 offset:32768
	ds_read_b128 v[88:91], v206 offset:34816
	ds_read_b128 v[124:127], v210 offset:49152
	s_waitcnt lgkmcnt(8)
	v_mfma_f32_16x16x32_bf16 v[40:43], v[76:79], v[100:103], v[40:43]
	v_mfma_f32_16x16x32_bf16 v[16:19], v[80:83], v[100:103], v[16:19]
	ds_read_b128 v[140:143], v210 offset:51200
	s_waitcnt lgkmcnt(8)
	v_mfma_f32_16x16x32_bf16 v[44:47], v[76:79], v[104:107], v[44:47]
	v_mfma_f32_16x16x32_bf16 v[20:23], v[80:83], v[104:107], v[20:23]
	ds_read_b128 v[144:147], v210 offset:53248
	s_waitcnt lgkmcnt(8)
	v_mfma_f32_16x16x32_bf16 v[48:51], v[76:79], v[108:111], v[48:51]
	v_mfma_f32_16x16x32_bf16 v[0:3], v[80:83], v[108:111], v[0:3]
	ds_read_b128 v[148:151], v210 offset:55296
	s_waitcnt lgkmcnt(8)
	v_mfma_f32_16x16x32_bf16 v[52:55], v[76:79], v[112:115], v[52:55]
	v_mfma_f32_16x16x32_bf16 v[8:11], v[80:83], v[112:115], v[8:11]
	ds_read_b128 v[92:95], v210 offset:57344
	s_waitcnt lgkmcnt(8)
	v_mfma_f32_16x16x32_bf16 v[56:59], v[76:79], v[116:119], v[56:59]
	v_mfma_f32_16x16x32_bf16 v[24:27], v[80:83], v[116:119], v[24:27]
	ds_read_b128 v[96:99], v210 offset:59392
	s_waitcnt lgkmcnt(8)
	v_mfma_f32_16x16x32_bf16 v[60:63], v[76:79], v[120:123], v[60:63]
	v_mfma_f32_16x16x32_bf16 v[28:31], v[80:83], v[120:123], v[28:31]
	ds_read_b128 v[100:103], v210 offset:61440
	s_waitcnt lgkmcnt(6)
	v_mfma_f32_16x16x32_bf16 v[32:35], v[84:87], v[124:127], v[32:35]
	v_mfma_f32_16x16x32_bf16 v[4:7], v[88:91], v[124:127], v[4:7]
	ds_read_b128 v[104:107], v210 offset:63488
	s_waitcnt lgkmcnt(6)
	v_mfma_f32_16x16x32_bf16 v[36:39], v[84:87], v[140:143], v[36:39]
	v_mfma_f32_16x16x32_bf16 v[12:15], v[88:91], v[140:143], v[12:15]
	s_waitcnt lgkmcnt(5)
	v_mfma_f32_16x16x32_bf16 v[40:43], v[84:87], v[144:147], v[40:43]
	v_mfma_f32_16x16x32_bf16 v[16:19], v[88:91], v[144:147], v[16:19]
	s_waitcnt lgkmcnt(4)
	v_mfma_f32_16x16x32_bf16 v[44:47], v[84:87], v[148:151], v[44:47]
	v_mfma_f32_16x16x32_bf16 v[20:23], v[88:91], v[148:151], v[20:23]
	s_waitcnt lgkmcnt(3)
	v_mfma_f32_16x16x32_bf16 v[48:51], v[84:87], v[92:95], v[48:51]
	v_mfma_f32_16x16x32_bf16 v[0:3], v[88:91], v[92:95], v[0:3]
	s_waitcnt lgkmcnt(2)
	v_mfma_f32_16x16x32_bf16 v[52:55], v[84:87], v[96:99], v[52:55]
	v_mfma_f32_16x16x32_bf16 v[8:11], v[88:91], v[96:99], v[8:11]
	s_waitcnt lgkmcnt(1)
	v_mfma_f32_16x16x32_bf16 v[56:59], v[84:87], v[100:103], v[56:59]
	v_mfma_f32_16x16x32_bf16 v[24:27], v[88:91], v[100:103], v[24:27]
	s_waitcnt lgkmcnt(0)
	v_mfma_f32_16x16x32_bf16 v[60:63], v[84:87], v[104:107], v[60:63]
	v_mfma_f32_16x16x32_bf16 v[28:31], v[88:91], v[104:107], v[28:31]
	s_nop 7
	s_nop 7
	s_waitcnt vmcnt(0) lgkmcnt(0)
	s_barrier
	s_mov_b64 s[58:59], -1
	s_cmp_lt_i32 s65, 4
	s_cbranch_scc1 .LBB0_434
	v_mul_f32_e32 v64, 0xbfb8aa3b, v32
	v_exp_f32_e32 v76, v64
	v_mul_f32_e32 v64, 0xbfb8aa3b, v33
	v_exp_f32_e32 v77, v64
	v_mul_f32_e32 v64, 0xbfb8aa3b, v34
	v_exp_f32_e32 v78, v64
	v_mul_f32_e32 v64, 0xbfb8aa3b, v35
	v_pk_add_f32 v[76:77], v[76:77], 1.0 op_sel_hi:[1,0]
	v_exp_f32_e32 v79, v64
	v_div_scale_f32 v64, s[56:57], v76, v76, v32
	v_rcp_f32_e32 v80, v64
	v_pk_add_f32 v[78:79], v[78:79], 1.0 op_sel_hi:[1,0]
	v_mul_f32_e32 v105, 0xbfb8aa3b, v59
	v_exp_f32_e32 v105, v105
	v_fma_f32 v81, -v64, v80, 1.0
	v_fmac_f32_e32 v80, v81, v80
	v_div_scale_f32 v81, vcc, v32, v76, v32
	v_mul_f32_e32 v82, v81, v80
	v_fma_f32 v83, -v64, v82, v81
	v_fmac_f32_e32 v82, v83, v80
	v_fma_f32 v64, -v64, v82, v81
	v_div_scale_f32 v81, s[56:57], v77, v77, v33
	v_rcp_f32_e32 v83, v81
	v_div_fmas_f32 v64, v64, v80, v82
	v_div_fixup_f32 v76, v64, v76, v32
	s_mov_b64 s[58:59], 0
	v_fma_f32 v64, -v81, v83, 1.0
	v_fmac_f32_e32 v83, v64, v83
	v_div_scale_f32 v64, vcc, v33, v77, v33
	v_mul_f32_e32 v80, v64, v83
	v_fma_f32 v82, -v81, v80, v64
	v_fmac_f32_e32 v80, v82, v83
	v_fma_f32 v64, -v81, v80, v64
	v_div_scale_f32 v81, s[56:57], v78, v78, v34
	v_rcp_f32_e32 v82, v81
	v_div_fmas_f32 v64, v64, v83, v80
	v_div_fixup_f32 v77, v64, v77, v33
	v_fma_f32 v64, -v81, v82, 1.0
	v_fmac_f32_e32 v82, v64, v82
	v_div_scale_f32 v64, vcc, v34, v78, v34
	v_mul_f32_e32 v80, v64, v82
	v_fma_f32 v83, -v81, v80, v64
	v_fmac_f32_e32 v80, v83, v82
	v_fma_f32 v64, -v81, v80, v64
	v_div_scale_f32 v81, s[56:57], v79, v79, v35
	v_rcp_f32_e32 v84, v81
	v_div_fmas_f32 v64, v64, v82, v80
	v_div_fixup_f32 v88, v64, v78, v34
	v_mul_f32_e32 v82, 0xbfb8aa3b, v38
	v_fma_f32 v64, -v81, v84, 1.0
	v_fmac_f32_e32 v84, v64, v84
	v_div_scale_f32 v64, vcc, v35, v79, v35
	v_mul_f32_e32 v78, v64, v84
	v_fma_f32 v80, -v81, v78, v64
	v_fmac_f32_e32 v78, v80, v84
	v_fma_f32 v64, -v81, v78, v64
	v_mul_f32_e32 v80, 0xbfb8aa3b, v36
	v_mul_f32_e32 v81, 0xbfb8aa3b, v37
	v_exp_f32_e32 v80, v80
	v_exp_f32_e32 v81, v81
	v_div_fmas_f32 v64, v64, v84, v78
	v_div_fixup_f32 v89, v64, v79, v35
	v_mul_f32_e32 v83, 0xbfb8aa3b, v39
	v_pk_add_f32 v[80:81], v[80:81], 1.0 op_sel_hi:[1,0]
	v_exp_f32_e32 v82, v82
	v_div_scale_f32 v85, s[56:57], v80, v80, v36
	v_rcp_f32_e32 v86, v85
	v_exp_f32_e32 v83, v83
	v_fma_f32 v64, -v85, v86, 1.0
	v_fmac_f32_e32 v86, v64, v86
	v_div_scale_f32 v64, vcc, v36, v80, v36
	v_mul_f32_e32 v78, v64, v86
	v_fma_f32 v79, -v85, v78, v64
	v_fmac_f32_e32 v78, v79, v86
	v_div_scale_f32 v79, s[56:57], v81, v81, v37
	v_rcp_f32_e32 v84, v79
	v_fma_f32 v64, -v85, v78, v64
	v_div_fmas_f32 v64, v64, v86, v78
	v_div_fixup_f32 v78, v64, v80, v36
	v_fma_f32 v64, -v79, v84, 1.0
	v_fmac_f32_e32 v84, v64, v84
	v_div_scale_f32 v64, vcc, v37, v81, v37
	v_mul_f32_e32 v80, v64, v84
	v_pk_add_f32 v[82:83], v[82:83], 1.0 op_sel_hi:[1,0]
	v_fma_f32 v85, -v79, v80, v64
	v_fmac_f32_e32 v80, v85, v84
	v_div_scale_f32 v85, s[56:57], v82, v82, v38
	v_rcp_f32_e32 v86, v85
	v_fma_f32 v64, -v79, v80, v64
	v_div_fmas_f32 v64, v64, v84, v80
	v_div_fixup_f32 v79, v64, v81, v37
	v_fma_f32 v64, -v85, v86, 1.0
	v_fmac_f32_e32 v86, v64, v86
	v_div_scale_f32 v64, vcc, v38, v82, v38
	v_mul_f32_e32 v80, v64, v86
	v_fma_f32 v81, -v85, v80, v64
	v_fmac_f32_e32 v80, v81, v86
	v_div_scale_f32 v81, s[56:57], v83, v83, v39
	v_rcp_f32_e32 v87, v81
	v_fma_f32 v64, -v85, v80, v64
	v_div_fmas_f32 v64, v64, v86, v80
	v_div_fixup_f32 v92, v64, v82, v38
	v_fma_f32 v64, -v81, v87, 1.0
	v_fmac_f32_e32 v87, v64, v87
	v_div_scale_f32 v64, vcc, v39, v83, v39
	v_mul_f32_e32 v82, v64, v87
	v_fma_f32 v80, -v81, v82, v64
	v_fmac_f32_e32 v82, v80, v87
	v_fma_f32 v64, -v81, v82, v64
	v_mul_f32_e32 v80, 0xbfb8aa3b, v40
	v_mul_f32_e32 v81, 0xbfb8aa3b, v41
	v_exp_f32_e32 v80, v80
	v_exp_f32_e32 v81, v81
	v_mul_f32_e32 v84, 0xbfb8aa3b, v42
	v_mul_f32_e32 v85, 0xbfb8aa3b, v43
	v_exp_f32_e32 v84, v84
	v_pk_add_f32 v[80:81], v[80:81], 1.0 op_sel_hi:[1,0]
	v_exp_f32_e32 v85, v85
	v_div_scale_f32 v86, s[56:57], v80, v80, v40
	v_rcp_f32_e32 v90, v86
	v_div_fmas_f32 v64, v64, v87, v82
	v_div_fixup_f32 v93, v64, v83, v39
	v_pk_add_f32 v[82:83], v[84:85], 1.0 op_sel_hi:[1,0]
	v_fma_f32 v64, -v86, v90, 1.0
	v_fmac_f32_e32 v90, v64, v90
	v_div_scale_f32 v64, vcc, v40, v80, v40
	v_mul_f32_e32 v84, v64, v90
	v_fma_f32 v85, -v86, v84, v64
	v_fmac_f32_e32 v84, v85, v90
	v_div_scale_f32 v85, s[56:57], v81, v81, v41
	v_fma_f32 v64, -v86, v84, v64
	v_rcp_f32_e32 v86, v85
	v_div_fmas_f32 v64, v64, v90, v84
	v_div_fixup_f32 v80, v64, v80, v40
	v_fma_f32 v64, -v85, v86, 1.0
	v_fmac_f32_e32 v86, v64, v86
	v_div_scale_f32 v64, vcc, v41, v81, v41
	v_mul_f32_e32 v84, v64, v86
	v_fma_f32 v87, -v85, v84, v64
	v_fmac_f32_e32 v84, v87, v86
	v_fma_f32 v64, -v85, v84, v64
	v_div_scale_f32 v85, s[56:57], v82, v82, v42
	v_rcp_f32_e32 v87, v85
	v_div_fmas_f32 v64, v64, v86, v84
	v_div_fixup_f32 v81, v64, v81, v41
	v_fma_f32 v64, -v85, v87, 1.0
	v_fmac_f32_e32 v87, v64, v87
	v_div_scale_f32 v64, vcc, v42, v82, v42
	v_mul_f32_e32 v84, v64, v87
	v_fma_f32 v86, -v85, v84, v64
	v_fmac_f32_e32 v84, v86, v87
	v_fma_f32 v64, -v85, v84, v64
	v_div_scale_f32 v85, s[56:57], v83, v83, v43
	v_rcp_f32_e32 v90, v85
	v_div_fmas_f32 v64, v64, v87, v84
	v_div_fixup_f32 v96, v64, v82, v42
	v_mul_f32_e32 v86, 0xbfb8aa3b, v46
	v_fma_f32 v64, -v85, v90, 1.0
	v_fmac_f32_e32 v90, v64, v90
	v_div_scale_f32 v64, vcc, v43, v83, v43
	v_mul_f32_e32 v82, v64, v90
	v_fma_f32 v84, -v85, v82, v64
	v_fmac_f32_e32 v82, v84, v90
	v_fma_f32 v64, -v85, v82, v64
	v_mul_f32_e32 v84, 0xbfb8aa3b, v44
	v_mul_f32_e32 v85, 0xbfb8aa3b, v45
	v_exp_f32_e32 v84, v84
	v_exp_f32_e32 v85, v85
	v_div_fmas_f32 v64, v64, v90, v82
	v_div_fixup_f32 v97, v64, v83, v43
	v_mul_f32_e32 v87, 0xbfb8aa3b, v47
	v_pk_add_f32 v[84:85], v[84:85], 1.0 op_sel_hi:[1,0]
	v_exp_f32_e32 v86, v86
	v_div_scale_f32 v91, s[56:57], v84, v84, v44
	v_rcp_f32_e32 v94, v91
	v_exp_f32_e32 v87, v87
	v_fma_f32 v64, -v91, v94, 1.0
	v_fmac_f32_e32 v94, v64, v94
	v_div_scale_f32 v64, vcc, v44, v84, v44
	v_mul_f32_e32 v82, v64, v94
	v_fma_f32 v83, -v91, v82, v64
	v_fmac_f32_e32 v82, v83, v94
	v_div_scale_f32 v83, s[56:57], v85, v85, v45
	v_rcp_f32_e32 v90, v83
	v_fma_f32 v64, -v91, v82, v64
	v_div_fmas_f32 v64, v64, v94, v82
	v_div_fixup_f32 v82, v64, v84, v44
	v_fma_f32 v64, -v83, v90, 1.0
	v_fmac_f32_e32 v90, v64, v90
	v_div_scale_f32 v64, vcc, v45, v85, v45
	v_mul_f32_e32 v84, v64, v90
	v_pk_add_f32 v[86:87], v[86:87], 1.0 op_sel_hi:[1,0]
	v_fma_f32 v91, -v83, v84, v64
	v_fmac_f32_e32 v84, v91, v90
	v_div_scale_f32 v91, s[56:57], v86, v86, v46
	v_rcp_f32_e32 v94, v91
	v_fma_f32 v64, -v83, v84, v64
	v_div_fmas_f32 v64, v64, v90, v84
	v_div_fixup_f32 v83, v64, v85, v45
	v_fma_f32 v64, -v91, v94, 1.0
	v_fmac_f32_e32 v94, v64, v94
	v_div_scale_f32 v64, vcc, v46, v86, v46
	v_mul_f32_e32 v84, v64, v94
	v_fma_f32 v85, -v91, v84, v64
	v_fmac_f32_e32 v84, v85, v94
	v_div_scale_f32 v85, s[56:57], v87, v87, v47
	v_rcp_f32_e32 v95, v85
	v_fma_f32 v64, -v91, v84, v64
	v_div_fmas_f32 v64, v64, v94, v84
	v_div_fixup_f32 v98, v64, v86, v46
	v_fma_f32 v64, -v85, v95, 1.0
	v_fmac_f32_e32 v95, v64, v95
	v_div_scale_f32 v64, vcc, v47, v87, v47
	v_mul_f32_e32 v86, v64, v95
	v_fma_f32 v84, -v85, v86, v64
	v_fmac_f32_e32 v86, v84, v95
	v_fma_f32 v64, -v85, v86, v64
	v_mul_f32_e32 v84, 0xbfb8aa3b, v48
	v_mul_f32_e32 v85, 0xbfb8aa3b, v49
	v_exp_f32_e32 v84, v84
	v_exp_f32_e32 v85, v85
	v_mul_f32_e32 v90, 0xbfb8aa3b, v50
	v_mul_f32_e32 v91, 0xbfb8aa3b, v51
	v_exp_f32_e32 v90, v90
	v_pk_add_f32 v[84:85], v[84:85], 1.0 op_sel_hi:[1,0]
	v_exp_f32_e32 v91, v91
	v_div_scale_f32 v94, s[56:57], v84, v84, v48
	v_rcp_f32_e32 v100, v94
	v_div_fmas_f32 v64, v64, v95, v86
	v_div_fixup_f32 v99, v64, v87, v47
	v_pk_add_f32 v[86:87], v[90:91], 1.0 op_sel_hi:[1,0]
	v_fma_f32 v64, -v94, v100, 1.0
	v_fmac_f32_e32 v100, v64, v100
	v_div_scale_f32 v64, vcc, v48, v84, v48
	v_mul_f32_e32 v90, v64, v100
	v_fma_f32 v91, -v94, v90, v64
	v_fmac_f32_e32 v90, v91, v100
	v_div_scale_f32 v91, s[56:57], v85, v85, v49
	v_fma_f32 v64, -v94, v90, v64
	v_rcp_f32_e32 v94, v91
	v_div_fmas_f32 v64, v64, v100, v90
	v_div_fixup_f32 v84, v64, v84, v48
	v_fma_f32 v64, -v91, v94, 1.0
	v_fmac_f32_e32 v94, v64, v94
	v_div_scale_f32 v64, vcc, v49, v85, v49
	v_mul_f32_e32 v90, v64, v94
	v_fma_f32 v95, -v91, v90, v64
	v_fmac_f32_e32 v90, v95, v94
	v_fma_f32 v64, -v91, v90, v64
	v_div_scale_f32 v91, s[56:57], v86, v86, v50
	v_rcp_f32_e32 v95, v91
	v_div_fmas_f32 v64, v64, v94, v90
	v_div_fixup_f32 v85, v64, v85, v49
	v_fma_f32 v64, -v91, v95, 1.0
	v_fmac_f32_e32 v95, v64, v95
	v_div_scale_f32 v64, vcc, v50, v86, v50
	v_mul_f32_e32 v90, v64, v95
	v_fma_f32 v94, -v91, v90, v64
	v_fmac_f32_e32 v90, v94, v95
	v_fma_f32 v64, -v91, v90, v64
	v_div_scale_f32 v91, s[56:57], v87, v87, v51
	v_rcp_f32_e32 v101, v91
	v_div_fmas_f32 v64, v64, v95, v90
	v_div_fixup_f32 v100, v64, v86, v50
	v_mul_f32_e32 v94, 0xbfb8aa3b, v54
	v_fma_f32 v64, -v91, v101, 1.0
	v_fmac_f32_e32 v101, v64, v101
	v_div_scale_f32 v64, vcc, v51, v87, v51
	v_mul_f32_e32 v86, v64, v101
	v_fma_f32 v90, -v91, v86, v64
	v_fmac_f32_e32 v86, v90, v101
	v_fma_f32 v64, -v91, v86, v64
	v_mul_f32_e32 v90, 0xbfb8aa3b, v52
	v_mul_f32_e32 v91, 0xbfb8aa3b, v53
	v_exp_f32_e32 v90, v90
	v_exp_f32_e32 v91, v91
	v_div_fmas_f32 v64, v64, v101, v86
	v_div_fixup_f32 v101, v64, v87, v51
	v_mul_f32_e32 v95, 0xbfb8aa3b, v55
	v_pk_add_f32 v[90:91], v[90:91], 1.0 op_sel_hi:[1,0]
	v_exp_f32_e32 v94, v94
	v_div_scale_f32 v102, s[56:57], v90, v90, v52
	v_rcp_f32_e32 v103, v102
	v_exp_f32_e32 v95, v95
	v_fma_f32 v64, -v102, v103, 1.0
	v_fmac_f32_e32 v103, v64, v103
	v_div_scale_f32 v64, vcc, v52, v90, v52
	v_mul_f32_e32 v86, v64, v103
	v_fma_f32 v87, -v102, v86, v64
	v_fmac_f32_e32 v86, v87, v103
	v_div_scale_f32 v87, s[56:57], v91, v91, v53
	v_fma_f32 v64, -v102, v86, v64
	v_rcp_f32_e32 v102, v87
	v_div_fmas_f32 v64, v64, v103, v86
	v_div_fixup_f32 v86, v64, v90, v52
	v_pk_add_f32 v[94:95], v[94:95], 1.0 op_sel_hi:[1,0]
	v_fma_f32 v64, -v87, v102, 1.0
	v_fmac_f32_e32 v102, v64, v102
	v_div_scale_f32 v64, vcc, v53, v91, v53
	v_mul_f32_e32 v90, v64, v102
	v_fma_f32 v103, -v87, v90, v64
	v_fmac_f32_e32 v90, v103, v102
	v_div_scale_f32 v103, s[56:57], v94, v94, v54
	v_rcp_f32_e32 v104, v103
	v_fma_f32 v64, -v87, v90, v64
	v_div_fmas_f32 v64, v64, v102, v90
	v_div_fixup_f32 v87, v64, v91, v53
	v_fma_f32 v64, -v103, v104, 1.0
	v_fmac_f32_e32 v104, v64, v104
	v_div_scale_f32 v64, vcc, v54, v94, v54
	v_mul_f32_e32 v90, v64, v104
	v_fma_f32 v91, -v103, v90, v64
	v_fmac_f32_e32 v90, v91, v104
	v_div_scale_f32 v91, s[56:57], v95, v95, v55
	v_fma_f32 v64, -v103, v90, v64
	v_rcp_f32_e32 v103, v91
	v_div_fmas_f32 v64, v64, v104, v90
	v_div_fixup_f32 v102, v64, v94, v54
	v_mul_f32_e32 v104, 0xbfb8aa3b, v58
	v_fma_f32 v64, -v91, v103, 1.0
	v_fmac_f32_e32 v103, v64, v103
	v_div_scale_f32 v64, vcc, v55, v95, v55
	v_mul_f32_e32 v94, v64, v103
	v_fma_f32 v90, -v91, v94, v64
	v_fmac_f32_e32 v94, v90, v103
	v_fma_f32 v64, -v91, v94, v64
	v_mul_f32_e32 v90, 0xbfb8aa3b, v56
	v_mul_f32_e32 v91, 0xbfb8aa3b, v57
	v_exp_f32_e32 v90, v90
	v_exp_f32_e32 v91, v91
	v_exp_f32_e32 v104, v104
	v_div_fmas_f32 v64, v64, v103, v94
	v_div_fixup_f32 v103, v64, v95, v55
	v_pk_add_f32 v[90:91], v[90:91], 1.0 op_sel_hi:[1,0]
	v_pk_add_f32 v[94:95], v[104:105], 1.0 op_sel_hi:[1,0]
	v_div_scale_f32 v106, s[56:57], v90, v90, v56
	v_rcp_f32_e32 v107, v106
	s_nop 0
	v_fma_f32 v64, -v106, v107, 1.0
	v_fmac_f32_e32 v107, v64, v107
	v_div_scale_f32 v64, vcc, v56, v90, v56
	v_mul_f32_e32 v104, v64, v107
	v_fma_f32 v105, -v106, v104, v64
	v_fmac_f32_e32 v104, v105, v107
	v_div_scale_f32 v105, s[56:57], v91, v91, v57
	v_fma_f32 v64, -v106, v104, v64
	v_rcp_f32_e32 v106, v105
	v_div_fmas_f32 v64, v64, v107, v104
	v_div_fixup_f32 v90, v64, v90, v56
	v_fma_f32 v64, -v105, v106, 1.0
	v_fmac_f32_e32 v106, v64, v106
	v_div_scale_f32 v64, vcc, v57, v91, v57
	v_mul_f32_e32 v104, v64, v106
	v_fma_f32 v107, -v105, v104, v64
	v_fmac_f32_e32 v104, v107, v106
	v_fma_f32 v64, -v105, v104, v64
	v_div_scale_f32 v105, s[56:57], v94, v94, v58
	v_rcp_f32_e32 v107, v105
	v_div_fmas_f32 v64, v64, v106, v104
	v_div_fixup_f32 v91, v64, v91, v57
	v_fma_f32 v64, -v105, v107, 1.0
	v_fmac_f32_e32 v107, v64, v107
	v_div_scale_f32 v64, vcc, v58, v94, v58
	v_mul_f32_e32 v104, v64, v107
	v_fma_f32 v106, -v105, v104, v64
	v_fmac_f32_e32 v104, v106, v107
	v_fma_f32 v64, -v105, v104, v64
	v_div_scale_f32 v105, s[56:57], v95, v95, v59
	v_rcp_f32_e32 v110, v105
	v_div_fmas_f32 v64, v64, v107, v104
	v_div_fixup_f32 v104, v64, v94, v58
	v_fma_f32 v64, -v105, v110, 1.0
	v_fmac_f32_e32 v110, v64, v110
	v_div_scale_f32 v64, vcc, v59, v95, v59
	v_mul_f32_e32 v94, v64, v110
	v_fma_f32 v106, -v105, v94, v64
	v_fmac_f32_e32 v94, v106, v110
	v_fma_f32 v64, -v105, v94, v64
	v_mul_f32_e32 v105, 0xbfb8aa3b, v60
	v_exp_f32_e32 v106, v105
	v_mul_f32_e32 v105, 0xbfb8aa3b, v61
	v_exp_f32_e32 v107, v105
	v_mul_f32_e32 v105, 0xbfb8aa3b, v62
	v_exp_f32_e32 v108, v105
	v_mul_f32_e32 v105, 0xbfb8aa3b, v63
	v_pk_add_f32 v[106:107], v[106:107], 1.0 op_sel_hi:[1,0]
	v_div_fmas_f32 v64, v64, v110, v94
	v_div_scale_f32 v111, s[56:57], v106, v106, v60
	v_rcp_f32_e32 v112, v111
	v_exp_f32_e32 v109, v105
	v_div_fixup_f32 v105, v64, v95, v59
	v_fma_f32 v64, -v111, v112, 1.0
	v_fmac_f32_e32 v112, v64, v112
	v_div_scale_f32 v64, vcc, v60, v106, v60
	v_mul_f32_e32 v94, v64, v112
	v_fma_f32 v95, -v111, v94, v64
	v_fmac_f32_e32 v94, v95, v112
	v_div_scale_f32 v95, s[56:57], v107, v107, v61
	v_rcp_f32_e32 v110, v95
	v_fma_f32 v64, -v111, v94, v64
	v_div_fmas_f32 v64, v64, v112, v94
	v_div_fixup_f32 v94, v64, v106, v60
	v_fma_f32 v64, -v95, v110, 1.0
	v_fmac_f32_e32 v110, v64, v110
	v_div_scale_f32 v64, vcc, v61, v107, v61
	v_mul_f32_e32 v106, v64, v110
	v_pk_add_f32 v[108:109], v[108:109], 1.0 op_sel_hi:[1,0]
	v_fma_f32 v111, -v95, v106, v64
	v_fmac_f32_e32 v106, v111, v110
	v_div_scale_f32 v111, s[56:57], v108, v108, v62
	v_rcp_f32_e32 v112, v111
	v_fma_f32 v64, -v95, v106, v64
	v_div_fmas_f32 v64, v64, v110, v106
	v_div_fixup_f32 v95, v64, v107, v61
	v_fma_f32 v64, -v111, v112, 1.0
	v_fmac_f32_e32 v112, v64, v112
	v_div_scale_f32 v64, vcc, v62, v108, v62
	v_mul_f32_e32 v106, v64, v112
	v_fma_f32 v107, -v111, v106, v64
	v_fmac_f32_e32 v106, v107, v112
	v_div_scale_f32 v107, s[56:57], v109, v109, v63
	v_rcp_f32_e32 v114, v107
	v_fma_f32 v64, -v111, v106, v64
	v_div_fmas_f32 v64, v64, v112, v106
	v_div_fixup_f32 v106, v64, v108, v62
	v_fma_f32 v64, -v107, v114, 1.0
	v_fmac_f32_e32 v114, v64, v114
	v_div_scale_f32 v64, vcc, v63, v109, v63
	v_mul_f32_e32 v108, v64, v114
	v_fma_f32 v110, -v107, v108, v64
	v_fmac_f32_e32 v108, v110, v114
	v_fma_f32 v64, -v107, v108, v64
	v_mul_f32_e32 v107, 0xbfb8aa3b, v4
	v_exp_f32_e32 v110, v107
	v_mul_f32_e32 v107, 0xbfb8aa3b, v5
	v_exp_f32_e32 v111, v107
	v_mul_f32_e32 v107, 0xbfb8aa3b, v6
	v_exp_f32_e32 v112, v107
	v_mul_f32_e32 v107, 0xbfb8aa3b, v7
	v_pk_add_f32 v[110:111], v[110:111], 1.0 op_sel_hi:[1,0]
	v_div_fmas_f32 v64, v64, v114, v108
	v_div_scale_f32 v115, s[56:57], v110, v110, v4
	v_rcp_f32_e32 v116, v115
	v_exp_f32_e32 v113, v107
	v_div_fixup_f32 v107, v64, v109, v63
	v_fma_f32 v64, -v115, v116, 1.0
	v_fmac_f32_e32 v116, v64, v116
	v_div_scale_f32 v64, vcc, v4, v110, v4
	v_mul_f32_e32 v108, v64, v116
	v_fma_f32 v109, -v115, v108, v64
	v_fmac_f32_e32 v108, v109, v116
	v_div_scale_f32 v109, s[56:57], v111, v111, v5
	v_rcp_f32_e32 v114, v109
	v_fma_f32 v64, -v115, v108, v64
	v_div_fmas_f32 v64, v64, v116, v108
	v_div_fixup_f32 v108, v64, v110, v4
	v_fma_f32 v64, -v109, v114, 1.0
	v_fmac_f32_e32 v114, v64, v114
	v_div_scale_f32 v64, vcc, v5, v111, v5
	v_mul_f32_e32 v110, v64, v114
	v_pk_add_f32 v[112:113], v[112:113], 1.0 op_sel_hi:[1,0]
	v_fma_f32 v115, -v109, v110, v64
	v_fmac_f32_e32 v110, v115, v114
	v_div_scale_f32 v115, s[56:57], v112, v112, v6
	v_rcp_f32_e32 v116, v115
	v_fma_f32 v64, -v109, v110, v64
	v_div_fmas_f32 v64, v64, v114, v110
	v_div_fixup_f32 v109, v64, v111, v5
	v_fma_f32 v64, -v115, v116, 1.0
	v_fmac_f32_e32 v116, v64, v116
	v_div_scale_f32 v64, vcc, v6, v112, v6
	v_mul_f32_e32 v110, v64, v116
	v_fma_f32 v111, -v115, v110, v64
	v_fmac_f32_e32 v110, v111, v116
	v_div_scale_f32 v111, s[56:57], v113, v113, v7
	v_rcp_f32_e32 v117, v111
	v_fma_f32 v64, -v115, v110, v64
	v_div_fmas_f32 v64, v64, v116, v110
	v_div_fixup_f32 v120, v64, v112, v6
	v_fma_f32 v64, -v111, v117, 1.0
	v_fmac_f32_e32 v117, v64, v117
	v_div_scale_f32 v64, vcc, v7, v113, v7
	v_mul_f32_e32 v112, v64, v117
	v_fma_f32 v110, -v111, v112, v64
	v_fmac_f32_e32 v112, v110, v117
	v_fma_f32 v64, -v111, v112, v64
	v_mul_f32_e32 v110, 0xbfb8aa3b, v12
	v_mul_f32_e32 v111, 0xbfb8aa3b, v13
	v_exp_f32_e32 v110, v110
	v_exp_f32_e32 v111, v111
	v_mul_f32_e32 v114, 0xbfb8aa3b, v14
	v_mul_f32_e32 v115, 0xbfb8aa3b, v15
	v_exp_f32_e32 v114, v114
	v_pk_add_f32 v[110:111], v[110:111], 1.0 op_sel_hi:[1,0]
	v_exp_f32_e32 v115, v115
	v_div_scale_f32 v116, s[56:57], v110, v110, v12
	v_rcp_f32_e32 v118, v116
	v_div_fmas_f32 v64, v64, v117, v112
	v_div_fixup_f32 v121, v64, v113, v7
	v_pk_add_f32 v[112:113], v[114:115], 1.0 op_sel_hi:[1,0]
	v_fma_f32 v64, -v116, v118, 1.0
	v_fmac_f32_e32 v118, v64, v118
	v_div_scale_f32 v64, vcc, v12, v110, v12
	v_mul_f32_e32 v114, v64, v118
	v_fma_f32 v115, -v116, v114, v64
	v_fmac_f32_e32 v114, v115, v118
	v_div_scale_f32 v115, s[56:57], v111, v111, v13
	v_fma_f32 v64, -v116, v114, v64
	v_rcp_f32_e32 v116, v115
	v_div_fmas_f32 v64, v64, v118, v114
	v_div_fixup_f32 v110, v64, v110, v12
	v_fma_f32 v64, -v115, v116, 1.0
	v_fmac_f32_e32 v116, v64, v116
	v_div_scale_f32 v64, vcc, v13, v111, v13
	v_mul_f32_e32 v114, v64, v116
	v_fma_f32 v117, -v115, v114, v64
	v_fmac_f32_e32 v114, v117, v116
	v_fma_f32 v64, -v115, v114, v64
	v_div_scale_f32 v115, s[56:57], v112, v112, v14
	v_rcp_f32_e32 v117, v115
	v_div_fmas_f32 v64, v64, v116, v114
	v_div_fixup_f32 v111, v64, v111, v13
	v_fma_f32 v64, -v115, v117, 1.0
	v_fmac_f32_e32 v117, v64, v117
	v_div_scale_f32 v64, vcc, v14, v112, v14
	v_mul_f32_e32 v114, v64, v117
	v_fma_f32 v116, -v115, v114, v64
	v_fmac_f32_e32 v114, v116, v117
	v_fma_f32 v64, -v115, v114, v64
	v_div_scale_f32 v115, s[56:57], v113, v113, v15
	v_rcp_f32_e32 v118, v115
	v_div_fmas_f32 v64, v64, v117, v114
	v_div_fixup_f32 v124, v64, v112, v14
	v_mul_f32_e32 v116, 0xbfb8aa3b, v18
	v_fma_f32 v64, -v115, v118, 1.0
	v_fmac_f32_e32 v118, v64, v118
	v_div_scale_f32 v64, vcc, v15, v113, v15
	v_mul_f32_e32 v112, v64, v118
	v_fma_f32 v114, -v115, v112, v64
	v_fmac_f32_e32 v112, v114, v118
	v_fma_f32 v64, -v115, v112, v64
	v_mul_f32_e32 v114, 0xbfb8aa3b, v16
	v_mul_f32_e32 v115, 0xbfb8aa3b, v17
	v_exp_f32_e32 v114, v114
	v_exp_f32_e32 v115, v115
	v_div_fmas_f32 v64, v64, v118, v112
	v_div_fixup_f32 v125, v64, v113, v15
	v_mul_f32_e32 v117, 0xbfb8aa3b, v19
	v_pk_add_f32 v[114:115], v[114:115], 1.0 op_sel_hi:[1,0]
	v_exp_f32_e32 v116, v116
	v_div_scale_f32 v119, s[56:57], v114, v114, v16
	v_rcp_f32_e32 v122, v119
	v_exp_f32_e32 v117, v117
	v_fma_f32 v64, -v119, v122, 1.0
	v_fmac_f32_e32 v122, v64, v122
	v_div_scale_f32 v64, vcc, v16, v114, v16
	v_mul_f32_e32 v112, v64, v122
	v_fma_f32 v113, -v119, v112, v64
	v_fmac_f32_e32 v112, v113, v122
	v_div_scale_f32 v113, s[56:57], v115, v115, v17
	v_rcp_f32_e32 v118, v113
	v_fma_f32 v64, -v119, v112, v64
	v_div_fmas_f32 v64, v64, v122, v112
	v_div_fixup_f32 v112, v64, v114, v16
	v_fma_f32 v64, -v113, v118, 1.0
	v_fmac_f32_e32 v118, v64, v118
	v_div_scale_f32 v64, vcc, v17, v115, v17
	v_mul_f32_e32 v114, v64, v118
	v_pk_add_f32 v[116:117], v[116:117], 1.0 op_sel_hi:[1,0]
	v_fma_f32 v119, -v113, v114, v64
	v_fmac_f32_e32 v114, v119, v118
	v_div_scale_f32 v119, s[56:57], v116, v116, v18
	v_rcp_f32_e32 v122, v119
	v_fma_f32 v64, -v113, v114, v64
	v_div_fmas_f32 v64, v64, v118, v114
	v_div_fixup_f32 v113, v64, v115, v17
	v_fma_f32 v64, -v119, v122, 1.0
	v_fmac_f32_e32 v122, v64, v122
	v_div_scale_f32 v64, vcc, v18, v116, v18
	v_mul_f32_e32 v114, v64, v122
	v_fma_f32 v115, -v119, v114, v64
	v_fmac_f32_e32 v114, v115, v122
	v_div_scale_f32 v115, s[56:57], v117, v117, v19
	v_rcp_f32_e32 v123, v115
	v_fma_f32 v64, -v119, v114, v64
	v_div_fmas_f32 v64, v64, v122, v114
	v_div_fixup_f32 v140, v64, v116, v18
	v_fma_f32 v64, -v115, v123, 1.0
	v_fmac_f32_e32 v123, v64, v123
	v_div_scale_f32 v64, vcc, v19, v117, v19
	v_mul_f32_e32 v116, v64, v123
	v_fma_f32 v114, -v115, v116, v64
	v_fmac_f32_e32 v116, v114, v123
	v_fma_f32 v64, -v115, v116, v64
	v_mul_f32_e32 v114, 0xbfb8aa3b, v20
	v_mul_f32_e32 v115, 0xbfb8aa3b, v21
	v_exp_f32_e32 v114, v114
	v_exp_f32_e32 v115, v115
	v_mul_f32_e32 v118, 0xbfb8aa3b, v22
	v_mul_f32_e32 v119, 0xbfb8aa3b, v23
	v_exp_f32_e32 v118, v118
	v_pk_add_f32 v[114:115], v[114:115], 1.0 op_sel_hi:[1,0]
	v_exp_f32_e32 v119, v119
	v_div_scale_f32 v122, s[56:57], v114, v114, v20
	v_rcp_f32_e32 v126, v122
	v_div_fmas_f32 v64, v64, v123, v116
	v_div_fixup_f32 v141, v64, v117, v19
	v_pk_add_f32 v[116:117], v[118:119], 1.0 op_sel_hi:[1,0]
	v_fma_f32 v64, -v122, v126, 1.0
	v_fmac_f32_e32 v126, v64, v126
	v_div_scale_f32 v64, vcc, v20, v114, v20
	v_mul_f32_e32 v118, v64, v126
	v_fma_f32 v119, -v122, v118, v64
	v_fmac_f32_e32 v118, v119, v126
	v_div_scale_f32 v119, s[56:57], v115, v115, v21
	v_fma_f32 v64, -v122, v118, v64
	v_rcp_f32_e32 v122, v119
	v_div_fmas_f32 v64, v64, v126, v118
	v_div_fixup_f32 v114, v64, v114, v20
	v_fma_f32 v64, -v119, v122, 1.0
	v_fmac_f32_e32 v122, v64, v122
	v_div_scale_f32 v64, vcc, v21, v115, v21
	v_mul_f32_e32 v118, v64, v122
	v_fma_f32 v123, -v119, v118, v64
	v_fmac_f32_e32 v118, v123, v122
	v_fma_f32 v64, -v119, v118, v64
	v_div_scale_f32 v119, s[56:57], v116, v116, v22
	v_rcp_f32_e32 v123, v119
	v_div_fmas_f32 v64, v64, v122, v118
	v_div_fixup_f32 v115, v64, v115, v21
	v_fma_f32 v64, -v119, v123, 1.0
	v_fmac_f32_e32 v123, v64, v123
	v_div_scale_f32 v64, vcc, v22, v116, v22
	v_mul_f32_e32 v118, v64, v123
	v_fma_f32 v122, -v119, v118, v64
	v_fmac_f32_e32 v118, v122, v123
	v_fma_f32 v64, -v119, v118, v64
	v_div_scale_f32 v119, s[56:57], v117, v117, v23
	v_rcp_f32_e32 v126, v119
	v_div_fmas_f32 v64, v64, v123, v118
	v_div_fixup_f32 v142, v64, v116, v22
	v_mul_f32_e32 v122, 0xbfb8aa3b, v2
	v_fma_f32 v64, -v119, v126, 1.0
	v_fmac_f32_e32 v126, v64, v126
	v_div_scale_f32 v64, vcc, v23, v117, v23
	v_mul_f32_e32 v116, v64, v126
	v_fma_f32 v118, -v119, v116, v64
	v_fmac_f32_e32 v116, v118, v126
	v_fma_f32 v64, -v119, v116, v64
	v_mul_f32_e32 v118, 0xbfb8aa3b, v0
	v_mul_f32_e32 v119, 0xbfb8aa3b, v1
	v_exp_f32_e32 v118, v118
	v_exp_f32_e32 v119, v119
	v_div_fmas_f32 v64, v64, v126, v116
	v_div_fixup_f32 v143, v64, v117, v23
	v_mul_f32_e32 v123, 0xbfb8aa3b, v3
	v_pk_add_f32 v[118:119], v[118:119], 1.0 op_sel_hi:[1,0]
	v_exp_f32_e32 v122, v122
	v_div_scale_f32 v127, s[56:57], v118, v118, v0
	v_rcp_f32_e32 v144, v127
	v_exp_f32_e32 v123, v123
	v_fma_f32 v64, -v127, v144, 1.0
	v_fmac_f32_e32 v144, v64, v144
	v_div_scale_f32 v64, vcc, v0, v118, v0
	v_mul_f32_e32 v116, v64, v144
	v_fma_f32 v117, -v127, v116, v64
	v_fmac_f32_e32 v116, v117, v144
	v_div_scale_f32 v117, s[56:57], v119, v119, v1
	v_rcp_f32_e32 v126, v117
	v_fma_f32 v64, -v127, v116, v64
	v_div_fmas_f32 v64, v64, v144, v116
	v_div_fixup_f32 v116, v64, v118, v0
	v_fma_f32 v64, -v117, v126, 1.0
	v_fmac_f32_e32 v126, v64, v126
	v_div_scale_f32 v64, vcc, v1, v119, v1
	v_mul_f32_e32 v118, v64, v126
	v_pk_add_f32 v[122:123], v[122:123], 1.0 op_sel_hi:[1,0]
	v_fma_f32 v127, -v117, v118, v64
	v_fmac_f32_e32 v118, v127, v126
	v_div_scale_f32 v127, s[56:57], v122, v122, v2
	v_rcp_f32_e32 v144, v127
	v_fma_f32 v64, -v117, v118, v64
	v_div_fmas_f32 v64, v64, v126, v118
	v_div_fixup_f32 v117, v64, v119, v1
	v_fma_f32 v64, -v127, v144, 1.0
	v_fmac_f32_e32 v144, v64, v144
	v_div_scale_f32 v64, vcc, v2, v122, v2
	v_mul_f32_e32 v118, v64, v144
	v_fma_f32 v119, -v127, v118, v64
	v_fmac_f32_e32 v118, v119, v144
	v_div_scale_f32 v119, s[56:57], v123, v123, v3
	v_rcp_f32_e32 v145, v119
	v_fma_f32 v64, -v127, v118, v64
	v_div_fmas_f32 v64, v64, v144, v118
	v_div_fixup_f32 v144, v64, v122, v2
	v_fma_f32 v64, -v119, v145, 1.0
	v_fmac_f32_e32 v145, v64, v145
	v_div_scale_f32 v64, vcc, v3, v123, v3
	v_mul_f32_e32 v122, v64, v145
	v_fma_f32 v118, -v119, v122, v64
	v_fmac_f32_e32 v122, v118, v145
	v_fma_f32 v64, -v119, v122, v64
	v_mul_f32_e32 v118, 0xbfb8aa3b, v8
	v_mul_f32_e32 v119, 0xbfb8aa3b, v9
	v_exp_f32_e32 v118, v118
	v_exp_f32_e32 v119, v119
	v_mul_f32_e32 v126, 0xbfb8aa3b, v10
	v_mul_f32_e32 v127, 0xbfb8aa3b, v11
	v_exp_f32_e32 v126, v126
	v_pk_add_f32 v[118:119], v[118:119], 1.0 op_sel_hi:[1,0]
	v_exp_f32_e32 v127, v127
	v_div_scale_f32 v146, s[56:57], v118, v118, v8
	v_rcp_f32_e32 v147, v146
	v_div_fmas_f32 v64, v64, v145, v122
	v_div_fixup_f32 v145, v64, v123, v3
	v_pk_add_f32 v[122:123], v[126:127], 1.0 op_sel_hi:[1,0]
	v_fma_f32 v64, -v146, v147, 1.0
	v_fmac_f32_e32 v147, v64, v147
	v_div_scale_f32 v64, vcc, v8, v118, v8
	v_mul_f32_e32 v126, v64, v147
	v_fma_f32 v127, -v146, v126, v64
	v_fmac_f32_e32 v126, v127, v147
	v_div_scale_f32 v127, s[56:57], v119, v119, v9
	v_fma_f32 v64, -v146, v126, v64
	v_rcp_f32_e32 v146, v127
	v_div_fmas_f32 v64, v64, v147, v126
	v_div_fixup_f32 v118, v64, v118, v8
	v_fma_f32 v64, -v127, v146, 1.0
	v_fmac_f32_e32 v146, v64, v146
	v_div_scale_f32 v64, vcc, v9, v119, v9
	v_mul_f32_e32 v126, v64, v146
	v_fma_f32 v147, -v127, v126, v64
	v_fmac_f32_e32 v126, v147, v146
	v_fma_f32 v64, -v127, v126, v64
	v_div_scale_f32 v127, s[56:57], v122, v122, v10
	v_rcp_f32_e32 v147, v127
	v_div_fmas_f32 v64, v64, v146, v126
	v_div_fixup_f32 v119, v64, v119, v9
	v_fma_f32 v64, -v127, v147, 1.0
	v_fmac_f32_e32 v147, v64, v147
	v_div_scale_f32 v64, vcc, v10, v122, v10
	v_mul_f32_e32 v126, v64, v147
	v_fma_f32 v146, -v127, v126, v64
	v_fmac_f32_e32 v126, v146, v147
	v_fma_f32 v64, -v127, v126, v64
	v_div_scale_f32 v127, s[56:57], v123, v123, v11
	v_rcp_f32_e32 v150, v127
	v_div_fmas_f32 v64, v64, v147, v126
	v_div_fixup_f32 v146, v64, v122, v10
	v_mul_f32_e32 v147, 0xbfb8aa3b, v26
	v_fma_f32 v64, -v127, v150, 1.0
	v_fmac_f32_e32 v150, v64, v150
	v_div_scale_f32 v64, vcc, v11, v123, v11
	v_mul_f32_e32 v122, v64, v150
	v_fma_f32 v126, -v127, v122, v64
	v_fmac_f32_e32 v122, v126, v150
	v_fma_f32 v64, -v127, v122, v64
	v_mul_f32_e32 v126, 0xbfb8aa3b, v24
	v_mul_f32_e32 v127, 0xbfb8aa3b, v25
	v_exp_f32_e32 v126, v126
	v_exp_f32_e32 v127, v127
	v_exp_f32_e32 v148, v147
	v_mul_f32_e32 v147, 0xbfb8aa3b, v27
	v_div_fmas_f32 v64, v64, v150, v122
	v_pk_add_f32 v[126:127], v[126:127], 1.0 op_sel_hi:[1,0]
	v_exp_f32_e32 v149, v147
	v_div_scale_f32 v151, s[56:57], v126, v126, v24
	v_rcp_f32_e32 v203, v151
	v_div_fixup_f32 v147, v64, v123, v11
	v_pk_add_f32 v[148:149], v[148:149], 1.0 op_sel_hi:[1,0]
	v_fma_f32 v64, -v151, v203, 1.0
	v_fmac_f32_e32 v203, v64, v203
	v_div_scale_f32 v64, vcc, v24, v126, v24
	v_mul_f32_e32 v122, v64, v203
	v_fma_f32 v123, -v151, v122, v64
	v_fmac_f32_e32 v122, v123, v203
	v_div_scale_f32 v123, s[56:57], v127, v127, v25
	v_rcp_f32_e32 v150, v123
	v_fma_f32 v64, -v151, v122, v64
	v_div_fmas_f32 v64, v64, v203, v122
	v_div_fixup_f32 v122, v64, v126, v24
	v_fma_f32 v64, -v123, v150, 1.0
	v_fmac_f32_e32 v150, v64, v150
	v_div_scale_f32 v64, vcc, v25, v127, v25
	v_mul_f32_e32 v126, v64, v150
	v_fma_f32 v151, -v123, v126, v64
	v_fmac_f32_e32 v126, v151, v150
	v_div_scale_f32 v151, s[56:57], v148, v148, v26
	v_rcp_f32_e32 v203, v151
	v_fma_f32 v64, -v123, v126, v64
	v_div_fmas_f32 v64, v64, v150, v126
	v_div_fixup_f32 v123, v64, v127, v25
	v_fma_f32 v64, -v151, v203, 1.0
	v_fmac_f32_e32 v203, v64, v203
	v_div_scale_f32 v64, vcc, v26, v148, v26
	v_mul_f32_e32 v126, v64, v203
	v_fma_f32 v127, -v151, v126, v64
	v_fmac_f32_e32 v126, v127, v203
	v_div_scale_f32 v127, s[56:57], v149, v149, v27
	v_rcp_f32_e32 v204, v127
	v_fma_f32 v64, -v151, v126, v64
	v_div_fmas_f32 v64, v64, v203, v126
	v_div_fixup_f32 v148, v64, v148, v26
	v_fma_f32 v64, -v127, v204, 1.0
	v_fmac_f32_e32 v204, v64, v204
	v_div_scale_f32 v64, vcc, v27, v149, v27
	v_mul_f32_e32 v203, v64, v204
	v_fma_f32 v126, -v127, v203, v64
	v_fmac_f32_e32 v203, v126, v204
	v_fma_f32 v64, -v127, v203, v64
	v_mul_f32_e32 v126, 0xbfb8aa3b, v28
	v_mul_f32_e32 v127, 0xbfb8aa3b, v29
	v_exp_f32_e32 v126, v126
	v_exp_f32_e32 v127, v127
	v_div_fmas_f32 v64, v64, v204, v203
	v_div_fixup_f32 v149, v64, v149, v27
	v_mul_f32_e32 v150, 0xbfb8aa3b, v30
	v_pk_add_f32 v[126:127], v[126:127], 1.0 op_sel_hi:[1,0]
	v_mul_f32_e32 v151, 0xbfb8aa3b, v31
	v_div_scale_f32 v205, s[56:57], v126, v126, v28
	v_rcp_f32_e32 v206, v205
	v_exp_f32_e32 v150, v150
	v_exp_f32_e32 v151, v151
	v_fma_f32 v64, -v205, v206, 1.0
	v_fmac_f32_e32 v206, v64, v206
	v_div_scale_f32 v64, vcc, v28, v126, v28
	v_mul_f32_e32 v203, v64, v206
	v_fma_f32 v204, -v205, v203, v64
	v_fmac_f32_e32 v203, v204, v206
	v_div_scale_f32 v204, s[56:57], v127, v127, v29
	v_fma_f32 v64, -v205, v203, v64
	v_rcp_f32_e32 v205, v204
	v_div_fmas_f32 v64, v64, v206, v203
	v_div_fixup_f32 v126, v64, v126, v28
	v_pk_add_f32 v[150:151], v[150:151], 1.0 op_sel_hi:[1,0]
	v_fma_f32 v64, -v204, v205, 1.0
	v_fmac_f32_e32 v205, v64, v205
	v_div_scale_f32 v64, vcc, v29, v127, v29
	v_mul_f32_e32 v203, v64, v205
	v_fma_f32 v206, -v204, v203, v64
	v_fmac_f32_e32 v203, v206, v205
	v_fma_f32 v64, -v204, v203, v64
	v_div_scale_f32 v204, s[56:57], v150, v150, v30
	v_rcp_f32_e32 v206, v204
	v_div_fmas_f32 v64, v64, v205, v203
	v_div_fixup_f32 v127, v64, v127, v29
	v_fma_f32 v64, -v204, v206, 1.0
	v_fmac_f32_e32 v206, v64, v206
	v_div_scale_f32 v64, vcc, v30, v150, v30
	v_mul_f32_e32 v203, v64, v206
	v_fma_f32 v205, -v204, v203, v64
	v_fmac_f32_e32 v203, v205, v206
	v_fma_f32 v64, -v204, v203, v64
	v_div_scale_f32 v204, s[56:57], v151, v151, v31
	v_rcp_f32_e32 v205, v204
	v_div_fmas_f32 v64, v64, v206, v203
	v_div_fixup_f32 v150, v64, v150, v30
	s_lshl_b64 s[56:57], s[0:1], 19
	v_fma_f32 v64, -v204, v205, 1.0
	v_fmac_f32_e32 v205, v64, v205
	v_div_scale_f32 v64, vcc, v31, v151, v31
	s_add_u32 s56, s36, s56
	v_mul_f32_e32 v203, v64, v205
	s_addc_u32 s57, s37, s57
	s_lshl_b32 s38, s4, 7
	v_fma_f32 v206, -v204, v203, v64
	s_lshl_b64 s[4:5], s[38:39], 1
	v_fmac_f32_e32 v203, v206, v205
	s_add_u32 s4, s56, s4
	v_fma_f32 v64, -v204, v203, v64
	s_addc_u32 s5, s57, s5
	v_div_fmas_f32 v64, v64, v205, v203
	s_add_u32 s56, s4, 0xffffe000
	v_div_fixup_f32 v151, v64, v151, v31
	s_addc_u32 s57, s5, -1
